# GEMM K-loops: second B fragment set read in the DMA-free groups (on top of late A DMAs)
# baseline (speedup 1.0000x reference)
.Lg161_loop:
	s_add_u32 s51, s50, 0x10000
	s_sub_u32 s53, s51, 0x28000
	s_cmp_ge_u32 s51, 0x28000
	s_cselect_b32 s51, s53, s51
	s_add_u32 s52, s49, 0x20000
	s_sub_u32 s53, s52, 0x28000
	s_cmp_ge_u32 s52, 0x28000
	s_cselect_b32 s52, s53, s52
	v_add_u32_e32 v137, s50, v135
	s_waitcnt lgkmcnt(4)
	s_waitcnt lgkmcnt(3)
	v_mfma_f32_16x16x32_bf16 v[112:115], v[164:167], v[224:227], v[112:115]
	v_mfma_f32_16x16x32_bf16 v[120:123], v[168:171], v[224:227], v[120:123]
	v_mfma_f32_16x16x32_bf16 v[96:99], v[172:175], v[224:227], v[96:99]
	v_mfma_f32_16x16x32_bf16 v[104:107], v[176:179], v[224:227], v[104:107]
	s_add_u32 m0, s51, s48
	s_nop 0
	global_load_lds_dwordx4 v139, s[64:65]
	s_add_u32 s64, s64, 0x80
	s_addc_u32 s65, s65, 0
	s_add_u32 s53, s51, s48
	s_add_u32 m0, s53, 0x2000
	s_nop 0
	global_load_lds_dwordx4 v139, s[66:67]
	s_add_u32 s66, s66, 0x80
	s_addc_u32 s67, s67, 0
	ds_read_b128 v[224:227], v136 offset:8192
	s_waitcnt lgkmcnt(3)
	v_mfma_f32_16x16x32_bf16 v[116:119], v[164:167], v[228:231], v[116:119]
	v_mfma_f32_16x16x32_bf16 v[124:127], v[168:171], v[228:231], v[124:127]
	v_mfma_f32_16x16x32_bf16 v[100:103], v[172:175], v[228:231], v[100:103]
	v_mfma_f32_16x16x32_bf16 v[108:111], v[176:179], v[228:231], v[108:111]
	s_add_u32 s53, s51, s48
	s_add_u32 m0, s53, 0x4000
	s_nop 0
	global_load_lds_dwordx4 v139, s[68:69]
	s_add_u32 s68, s68, 0x80
	s_addc_u32 s69, s69, 0
	s_add_u32 s53, s51, s48
	s_add_u32 m0, s53, 0x6000
	s_nop 0
	global_load_lds_dwordx4 v139, s[70:71]
	s_add_u32 s70, s70, 0x80
	s_addc_u32 s71, s71, 0
	ds_read_b128 v[228:231], v136 offset:10240
	s_waitcnt lgkmcnt(3)
	v_mfma_f32_16x16x32_bf16 v[80:83], v[164:167], v[232:235], v[80:83]
	v_mfma_f32_16x16x32_bf16 v[88:91], v[168:171], v[232:235], v[88:91]
	v_mfma_f32_16x16x32_bf16 v[64:67], v[172:175], v[232:235], v[64:67]
	v_mfma_f32_16x16x32_bf16 v[72:75], v[176:179], v[232:235], v[72:75]
	ds_read_b128 v[232:235], v136 offset:12288
	s_waitcnt lgkmcnt(3)
	v_mfma_f32_16x16x32_bf16 v[84:87], v[164:167], v[236:239], v[84:87]
	v_mfma_f32_16x16x32_bf16 v[92:95], v[168:171], v[236:239], v[92:95]
	v_mfma_f32_16x16x32_bf16 v[68:71], v[172:175], v[236:239], v[68:71]
	v_mfma_f32_16x16x32_bf16 v[76:79], v[176:179], v[236:239], v[76:79]
	ds_read_b128 v[236:239], v136 offset:14336
	v_add_u32_e32 v136, s49, v133
	s_waitcnt lgkmcnt(3)
	v_mfma_f32_16x16x32_bf16 v[48:51], v[164:167], v[224:227], v[48:51]
	v_mfma_f32_16x16x32_bf16 v[56:59], v[168:171], v[224:227], v[56:59]
	v_mfma_f32_16x16x32_bf16 v[32:35], v[172:175], v[224:227], v[32:35]
	v_mfma_f32_16x16x32_bf16 v[40:43], v[176:179], v[224:227], v[40:43]
	ds_read_b128 v[224:227], v136
	ds_read_b128 v[180:183], v137
	s_waitcnt lgkmcnt(4)
	v_mfma_f32_16x16x32_bf16 v[52:55], v[164:167], v[228:231], v[52:55]
	v_mfma_f32_16x16x32_bf16 v[60:63], v[168:171], v[228:231], v[60:63]
	v_mfma_f32_16x16x32_bf16 v[36:39], v[172:175], v[228:231], v[36:39]
	v_mfma_f32_16x16x32_bf16 v[44:47], v[176:179], v[228:231], v[44:47]
	ds_read_b128 v[228:231], v136 offset:2048
	ds_read_b128 v[212:215], v137 offset:2048
	s_waitcnt lgkmcnt(5)
	v_mfma_f32_16x16x32_bf16 v[16:19], v[164:167], v[232:235], v[16:19]
	v_mfma_f32_16x16x32_bf16 v[24:27], v[168:171], v[232:235], v[24:27]
	v_mfma_f32_16x16x32_bf16 v[0:3], v[172:175], v[232:235], v[0:3]
	v_mfma_f32_16x16x32_bf16 v[8:11], v[176:179], v[232:235], v[8:11]
	ds_read_b128 v[232:235], v136 offset:4096
	ds_read_b128 v[216:219], v137 offset:4096
	s_waitcnt lgkmcnt(6)
	v_mfma_f32_16x16x32_bf16 v[20:23], v[164:167], v[236:239], v[20:23]
	v_mfma_f32_16x16x32_bf16 v[28:31], v[168:171], v[236:239], v[28:31]
	v_mfma_f32_16x16x32_bf16 v[4:7], v[172:175], v[236:239], v[4:7]
	v_mfma_f32_16x16x32_bf16 v[12:15], v[176:179], v[236:239], v[12:15]
	ds_read_b128 v[236:239], v136 offset:6144
	ds_read_b128 v[220:223], v137 offset:6144
	s_waitcnt lgkmcnt(0)
	v_mfma_f32_16x16x32_bf16 v[112:115], v[180:183], v[224:227], v[112:115]
	v_mfma_f32_16x16x32_bf16 v[120:123], v[212:215], v[224:227], v[120:123]
	v_mfma_f32_16x16x32_bf16 v[96:99], v[216:219], v[224:227], v[96:99]
	v_mfma_f32_16x16x32_bf16 v[104:107], v[220:223], v[224:227], v[104:107]
	ds_read_b128 v[224:227], v136 offset:8192
	v_mfma_f32_16x16x32_bf16 v[116:119], v[180:183], v[228:231], v[116:119]
	v_mfma_f32_16x16x32_bf16 v[124:127], v[212:215], v[228:231], v[124:127]
	v_mfma_f32_16x16x32_bf16 v[100:103], v[216:219], v[228:231], v[100:103]
	v_mfma_f32_16x16x32_bf16 v[108:111], v[220:223], v[228:231], v[108:111]
	ds_read_b128 v[228:231], v136 offset:10240
	v_mfma_f32_16x16x32_bf16 v[80:83], v[180:183], v[232:235], v[80:83]
	v_mfma_f32_16x16x32_bf16 v[88:91], v[212:215], v[232:235], v[88:91]
	v_mfma_f32_16x16x32_bf16 v[64:67], v[216:219], v[232:235], v[64:67]
	v_mfma_f32_16x16x32_bf16 v[72:75], v[220:223], v[232:235], v[72:75]
	ds_read_b128 v[232:235], v136 offset:12288
	v_mfma_f32_16x16x32_bf16 v[84:87], v[180:183], v[236:239], v[84:87]
	v_mfma_f32_16x16x32_bf16 v[92:95], v[212:215], v[236:239], v[92:95]
	v_mfma_f32_16x16x32_bf16 v[68:71], v[216:219], v[236:239], v[68:71]
	v_mfma_f32_16x16x32_bf16 v[76:79], v[220:223], v[236:239], v[76:79]
	ds_read_b128 v[236:239], v136 offset:14336
	s_waitcnt lgkmcnt(3)
	v_mfma_f32_16x16x32_bf16 v[48:51], v[180:183], v[224:227], v[48:51]
	v_mfma_f32_16x16x32_bf16 v[56:59], v[212:215], v[224:227], v[56:59]
	v_mfma_f32_16x16x32_bf16 v[32:35], v[216:219], v[224:227], v[32:35]
	v_mfma_f32_16x16x32_bf16 v[40:43], v[220:223], v[224:227], v[40:43]
	s_add_u32 m0, s52, s48
	s_nop 0
	global_load_lds_dwordx4 v138, s[56:57]
	s_add_u32 s56, s56, 0x80
	s_addc_u32 s57, s57, 0
	s_add_u32 s53, s52, s48
	s_add_u32 m0, s53, 0x2000
	s_nop 0
	global_load_lds_dwordx4 v138, s[58:59]
	s_add_u32 s58, s58, 0x80
	s_addc_u32 s59, s59, 0
	s_waitcnt lgkmcnt(2)
	v_mfma_f32_16x16x32_bf16 v[52:55], v[180:183], v[228:231], v[52:55]
	v_mfma_f32_16x16x32_bf16 v[60:63], v[212:215], v[228:231], v[60:63]
	v_mfma_f32_16x16x32_bf16 v[36:39], v[216:219], v[228:231], v[36:39]
	v_mfma_f32_16x16x32_bf16 v[44:47], v[220:223], v[228:231], v[44:47]
	s_add_u32 s53, s52, s48
	s_add_u32 m0, s53, 0x4000
	s_nop 0
	global_load_lds_dwordx4 v138, s[60:61]
	s_add_u32 s60, s60, 0x80
	s_addc_u32 s61, s61, 0
	s_add_u32 s53, s52, s48
	s_add_u32 m0, s53, 0x6000
	s_nop 0
	global_load_lds_dwordx4 v138, s[62:63]
	s_add_u32 s62, s62, 0x80
	s_addc_u32 s63, s63, 0
	s_waitcnt lgkmcnt(1)
	v_mfma_f32_16x16x32_bf16 v[16:19], v[180:183], v[232:235], v[16:19]
	v_mfma_f32_16x16x32_bf16 v[24:27], v[212:215], v[232:235], v[24:27]
	v_mfma_f32_16x16x32_bf16 v[0:3], v[216:219], v[232:235], v[0:3]
	v_mfma_f32_16x16x32_bf16 v[8:11], v[220:223], v[232:235], v[8:11]
	s_waitcnt lgkmcnt(0)
	s_add_u32 s4, s4, 0x80
	s_addc_u32 s5, s5, 0
	s_add_u32 s49, s49, 0x10000
	s_sub_u32 s53, s49, 0x28000
	s_cmp_ge_u32 s49, 0x28000
	s_cselect_b32 s49, s53, s49
	s_mov_b32 s50, s51
	s_waitcnt vmcnt(4)
	s_barrier
	v_add_u32_e32 v137, s50, v134
	v_add_u32_e32 v136, s49, v132
	ds_read_b128 v[164:167], v137
	ds_read_b128 v[168:171], v137 offset:2048
	ds_read_b128 v[172:175], v137 offset:4096
	ds_read_b128 v[176:179], v137 offset:6144
	ds_read_b128 v[224:227], v136
	ds_read_b128 v[228:231], v136 offset:2048
	ds_read_b128 v[232:235], v136 offset:4096
	v_mfma_f32_16x16x32_bf16 v[20:23], v[180:183], v[236:239], v[20:23]
	v_mfma_f32_16x16x32_bf16 v[28:31], v[212:215], v[236:239], v[28:31]
	v_mfma_f32_16x16x32_bf16 v[4:7], v[216:219], v[236:239], v[4:7]
	v_mfma_f32_16x16x32_bf16 v[12:15], v[220:223], v[236:239], v[12:15]
	ds_read_b128 v[236:239], v136 offset:6144
	s_cmpk_lg_i32 s4, 0xf00
	s_cbranch_scc1 .Lg161_loop
	s_add_u32 s51, s50, 0x10000
	s_sub_u32 s53, s51, 0x28000
	s_cmp_ge_u32 s51, 0x28000
	s_cselect_b32 s51, s53, s51
	v_add_u32_e32 v137, s50, v135
	s_waitcnt lgkmcnt(4)
	s_waitcnt lgkmcnt(3)
	v_mfma_f32_16x16x32_bf16 v[112:115], v[164:167], v[224:227], v[112:115]
	v_mfma_f32_16x16x32_bf16 v[120:123], v[168:171], v[224:227], v[120:123]
	v_mfma_f32_16x16x32_bf16 v[96:99], v[172:175], v[224:227], v[96:99]
	v_mfma_f32_16x16x32_bf16 v[104:107], v[176:179], v[224:227], v[104:107]
	s_add_u32 m0, s51, s48
	s_nop 0
	global_load_lds_dwordx4 v139, s[64:65]
	s_add_u32 s64, s64, 0x80
	s_addc_u32 s65, s65, 0
	s_add_u32 s53, s51, s48
	s_add_u32 m0, s53, 0x2000
	s_nop 0
	global_load_lds_dwordx4 v139, s[66:67]
	s_add_u32 s66, s66, 0x80
	s_addc_u32 s67, s67, 0
	ds_read_b128 v[224:227], v136 offset:8192
	s_waitcnt lgkmcnt(3)
	v_mfma_f32_16x16x32_bf16 v[116:119], v[164:167], v[228:231], v[116:119]
	v_mfma_f32_16x16x32_bf16 v[124:127], v[168:171], v[228:231], v[124:127]
	v_mfma_f32_16x16x32_bf16 v[100:103], v[172:175], v[228:231], v[100:103]
	v_mfma_f32_16x16x32_bf16 v[108:111], v[176:179], v[228:231], v[108:111]
	s_add_u32 s53, s51, s48
	s_add_u32 m0, s53, 0x4000
	s_nop 0
	global_load_lds_dwordx4 v139, s[68:69]
	s_add_u32 s68, s68, 0x80
	s_addc_u32 s69, s69, 0
	s_add_u32 s53, s51, s48
	s_add_u32 m0, s53, 0x6000
	s_nop 0
	global_load_lds_dwordx4 v139, s[70:71]
	s_add_u32 s70, s70, 0x80
	s_addc_u32 s71, s71, 0
	ds_read_b128 v[228:231], v136 offset:10240
	s_waitcnt lgkmcnt(3)
	v_mfma_f32_16x16x32_bf16 v[80:83], v[164:167], v[232:235], v[80:83]
	v_mfma_f32_16x16x32_bf16 v[88:91], v[168:171], v[232:235], v[88:91]
	v_mfma_f32_16x16x32_bf16 v[64:67], v[172:175], v[232:235], v[64:67]
	v_mfma_f32_16x16x32_bf16 v[72:75], v[176:179], v[232:235], v[72:75]
	ds_read_b128 v[232:235], v136 offset:12288
	s_waitcnt lgkmcnt(3)
	v_mfma_f32_16x16x32_bf16 v[84:87], v[164:167], v[236:239], v[84:87]
	v_mfma_f32_16x16x32_bf16 v[92:95], v[168:171], v[236:239], v[92:95]
	v_mfma_f32_16x16x32_bf16 v[68:71], v[172:175], v[236:239], v[68:71]
	v_mfma_f32_16x16x32_bf16 v[76:79], v[176:179], v[236:239], v[76:79]
	ds_read_b128 v[236:239], v136 offset:14336
	v_add_u32_e32 v136, s49, v133
	s_waitcnt lgkmcnt(3)
	v_mfma_f32_16x16x32_bf16 v[48:51], v[164:167], v[224:227], v[48:51]
	v_mfma_f32_16x16x32_bf16 v[56:59], v[168:171], v[224:227], v[56:59]
	v_mfma_f32_16x16x32_bf16 v[32:35], v[172:175], v[224:227], v[32:35]
	v_mfma_f32_16x16x32_bf16 v[40:43], v[176:179], v[224:227], v[40:43]
	ds_read_b128 v[224:227], v136
	ds_read_b128 v[180:183], v137
	s_waitcnt lgkmcnt(4)
	v_mfma_f32_16x16x32_bf16 v[52:55], v[164:167], v[228:231], v[52:55]
	v_mfma_f32_16x16x32_bf16 v[60:63], v[168:171], v[228:231], v[60:63]
	v_mfma_f32_16x16x32_bf16 v[36:39], v[172:175], v[228:231], v[36:39]
	v_mfma_f32_16x16x32_bf16 v[44:47], v[176:179], v[228:231], v[44:47]
	ds_read_b128 v[228:231], v136 offset:2048
	ds_read_b128 v[212:215], v137 offset:2048
	s_waitcnt lgkmcnt(5)
	v_mfma_f32_16x16x32_bf16 v[16:19], v[164:167], v[232:235], v[16:19]
	v_mfma_f32_16x16x32_bf16 v[24:27], v[168:171], v[232:235], v[24:27]
	v_mfma_f32_16x16x32_bf16 v[0:3], v[172:175], v[232:235], v[0:3]
	v_mfma_f32_16x16x32_bf16 v[8:11], v[176:179], v[232:235], v[8:11]
	ds_read_b128 v[232:235], v136 offset:4096
	ds_read_b128 v[216:219], v137 offset:4096
	s_waitcnt lgkmcnt(6)
	v_mfma_f32_16x16x32_bf16 v[20:23], v[164:167], v[236:239], v[20:23]
	v_mfma_f32_16x16x32_bf16 v[28:31], v[168:171], v[236:239], v[28:31]
	v_mfma_f32_16x16x32_bf16 v[4:7], v[172:175], v[236:239], v[4:7]
	v_mfma_f32_16x16x32_bf16 v[12:15], v[176:179], v[236:239], v[12:15]
	ds_read_b128 v[236:239], v136 offset:6144
	ds_read_b128 v[220:223], v137 offset:6144
	s_waitcnt lgkmcnt(0)
	v_mfma_f32_16x16x32_bf16 v[112:115], v[180:183], v[224:227], v[112:115]
	v_mfma_f32_16x16x32_bf16 v[120:123], v[212:215], v[224:227], v[120:123]
	v_mfma_f32_16x16x32_bf16 v[96:99], v[216:219], v[224:227], v[96:99]
	v_mfma_f32_16x16x32_bf16 v[104:107], v[220:223], v[224:227], v[104:107]
	ds_read_b128 v[224:227], v136 offset:8192
	v_mfma_f32_16x16x32_bf16 v[116:119], v[180:183], v[228:231], v[116:119]
	v_mfma_f32_16x16x32_bf16 v[124:127], v[212:215], v[228:231], v[124:127]
	v_mfma_f32_16x16x32_bf16 v[100:103], v[216:219], v[228:231], v[100:103]
	v_mfma_f32_16x16x32_bf16 v[108:111], v[220:223], v[228:231], v[108:111]
	ds_read_b128 v[228:231], v136 offset:10240
	v_mfma_f32_16x16x32_bf16 v[80:83], v[180:183], v[232:235], v[80:83]
	v_mfma_f32_16x16x32_bf16 v[88:91], v[212:215], v[232:235], v[88:91]
	v_mfma_f32_16x16x32_bf16 v[64:67], v[216:219], v[232:235], v[64:67]
	v_mfma_f32_16x16x32_bf16 v[72:75], v[220:223], v[232:235], v[72:75]
	ds_read_b128 v[232:235], v136 offset:12288
	v_mfma_f32_16x16x32_bf16 v[84:87], v[180:183], v[236:239], v[84:87]
	v_mfma_f32_16x16x32_bf16 v[92:95], v[212:215], v[236:239], v[92:95]
	v_mfma_f32_16x16x32_bf16 v[68:71], v[216:219], v[236:239], v[68:71]
	v_mfma_f32_16x16x32_bf16 v[76:79], v[220:223], v[236:239], v[76:79]
	ds_read_b128 v[236:239], v136 offset:14336
	s_waitcnt lgkmcnt(3)
	v_mfma_f32_16x16x32_bf16 v[48:51], v[180:183], v[224:227], v[48:51]
	v_mfma_f32_16x16x32_bf16 v[56:59], v[212:215], v[224:227], v[56:59]
	v_mfma_f32_16x16x32_bf16 v[32:35], v[216:219], v[224:227], v[32:35]
	v_mfma_f32_16x16x32_bf16 v[40:43], v[220:223], v[224:227], v[40:43]
	s_waitcnt lgkmcnt(2)
	v_mfma_f32_16x16x32_bf16 v[52:55], v[180:183], v[228:231], v[52:55]
	v_mfma_f32_16x16x32_bf16 v[60:63], v[212:215], v[228:231], v[60:63]
	v_mfma_f32_16x16x32_bf16 v[36:39], v[216:219], v[228:231], v[36:39]
	v_mfma_f32_16x16x32_bf16 v[44:47], v[220:223], v[228:231], v[44:47]
	s_waitcnt lgkmcnt(1)
	v_mfma_f32_16x16x32_bf16 v[16:19], v[180:183], v[232:235], v[16:19]
	v_mfma_f32_16x16x32_bf16 v[24:27], v[212:215], v[232:235], v[24:27]
	v_mfma_f32_16x16x32_bf16 v[0:3], v[216:219], v[232:235], v[0:3]
	v_mfma_f32_16x16x32_bf16 v[8:11], v[220:223], v[232:235], v[8:11]
	s_waitcnt lgkmcnt(0)
	s_add_u32 s4, s4, 0x80
	s_addc_u32 s5, s5, 0
	s_add_u32 s49, s49, 0x10000
	s_sub_u32 s53, s49, 0x28000
	s_cmp_ge_u32 s49, 0x28000
	s_cselect_b32 s49, s53, s49
	s_mov_b32 s50, s51
	s_waitcnt vmcnt(0)
	s_barrier
	v_add_u32_e32 v137, s50, v134
	v_add_u32_e32 v136, s49, v132
	ds_read_b128 v[164:167], v137
	ds_read_b128 v[168:171], v137 offset:2048
	ds_read_b128 v[172:175], v137 offset:4096
	ds_read_b128 v[176:179], v137 offset:6144
	ds_read_b128 v[224:227], v136
	ds_read_b128 v[228:231], v136 offset:2048
	ds_read_b128 v[232:235], v136 offset:4096
	v_mfma_f32_16x16x32_bf16 v[20:23], v[180:183], v[236:239], v[20:23]
	v_mfma_f32_16x16x32_bf16 v[28:31], v[212:215], v[236:239], v[28:31]
	v_mfma_f32_16x16x32_bf16 v[4:7], v[216:219], v[236:239], v[4:7]
	v_mfma_f32_16x16x32_bf16 v[12:15], v[220:223], v[236:239], v[12:15]
	ds_read_b128 v[236:239], v136 offset:6144
	v_add_u32_e32 v137, s50, v135
	s_waitcnt lgkmcnt(4)
	s_waitcnt lgkmcnt(3)
	v_mfma_f32_16x16x32_bf16 v[112:115], v[164:167], v[224:227], v[112:115]
	v_mfma_f32_16x16x32_bf16 v[120:123], v[168:171], v[224:227], v[120:123]
	v_mfma_f32_16x16x32_bf16 v[96:99], v[172:175], v[224:227], v[96:99]
	v_mfma_f32_16x16x32_bf16 v[104:107], v[176:179], v[224:227], v[104:107]
	ds_read_b128 v[224:227], v136 offset:8192
	s_waitcnt lgkmcnt(3)
	v_mfma_f32_16x16x32_bf16 v[116:119], v[164:167], v[228:231], v[116:119]
	v_mfma_f32_16x16x32_bf16 v[124:127], v[168:171], v[228:231], v[124:127]
	v_mfma_f32_16x16x32_bf16 v[100:103], v[172:175], v[228:231], v[100:103]
	v_mfma_f32_16x16x32_bf16 v[108:111], v[176:179], v[228:231], v[108:111]
	ds_read_b128 v[228:231], v136 offset:10240
	s_waitcnt lgkmcnt(3)
	v_mfma_f32_16x16x32_bf16 v[80:83], v[164:167], v[232:235], v[80:83]
	v_mfma_f32_16x16x32_bf16 v[88:91], v[168:171], v[232:235], v[88:91]
	v_mfma_f32_16x16x32_bf16 v[64:67], v[172:175], v[232:235], v[64:67]
	v_mfma_f32_16x16x32_bf16 v[72:75], v[176:179], v[232:235], v[72:75]
	ds_read_b128 v[232:235], v136 offset:12288
	s_waitcnt lgkmcnt(3)
	v_mfma_f32_16x16x32_bf16 v[84:87], v[164:167], v[236:239], v[84:87]
	v_mfma_f32_16x16x32_bf16 v[92:95], v[168:171], v[236:239], v[92:95]
	v_mfma_f32_16x16x32_bf16 v[68:71], v[172:175], v[236:239], v[68:71]
	v_mfma_f32_16x16x32_bf16 v[76:79], v[176:179], v[236:239], v[76:79]
	ds_read_b128 v[236:239], v136 offset:14336
	v_add_u32_e32 v136, s49, v133
	s_waitcnt lgkmcnt(3)
	v_mfma_f32_16x16x32_bf16 v[48:51], v[164:167], v[224:227], v[48:51]
	v_mfma_f32_16x16x32_bf16 v[56:59], v[168:171], v[224:227], v[56:59]
	v_mfma_f32_16x16x32_bf16 v[32:35], v[172:175], v[224:227], v[32:35]
	v_mfma_f32_16x16x32_bf16 v[40:43], v[176:179], v[224:227], v[40:43]
	ds_read_b128 v[224:227], v136
	ds_read_b128 v[180:183], v137
	s_waitcnt lgkmcnt(4)
	v_mfma_f32_16x16x32_bf16 v[52:55], v[164:167], v[228:231], v[52:55]
	v_mfma_f32_16x16x32_bf16 v[60:63], v[168:171], v[228:231], v[60:63]
	v_mfma_f32_16x16x32_bf16 v[36:39], v[172:175], v[228:231], v[36:39]
	v_mfma_f32_16x16x32_bf16 v[44:47], v[176:179], v[228:231], v[44:47]
	ds_read_b128 v[228:231], v136 offset:2048
	ds_read_b128 v[212:215], v137 offset:2048
	s_waitcnt lgkmcnt(5)
	v_mfma_f32_16x16x32_bf16 v[16:19], v[164:167], v[232:235], v[16:19]
	v_mfma_f32_16x16x32_bf16 v[24:27], v[168:171], v[232:235], v[24:27]
	v_mfma_f32_16x16x32_bf16 v[0:3], v[172:175], v[232:235], v[0:3]
	v_mfma_f32_16x16x32_bf16 v[8:11], v[176:179], v[232:235], v[8:11]
	ds_read_b128 v[232:235], v136 offset:4096
	ds_read_b128 v[216:219], v137 offset:4096
	s_waitcnt lgkmcnt(6)
	v_mfma_f32_16x16x32_bf16 v[20:23], v[164:167], v[236:239], v[20:23]
	v_mfma_f32_16x16x32_bf16 v[28:31], v[168:171], v[236:239], v[28:31]
	v_mfma_f32_16x16x32_bf16 v[4:7], v[172:175], v[236:239], v[4:7]
	v_mfma_f32_16x16x32_bf16 v[12:15], v[176:179], v[236:239], v[12:15]
	ds_read_b128 v[236:239], v136 offset:6144
	ds_read_b128 v[220:223], v137 offset:6144
	s_waitcnt lgkmcnt(0)
	v_mfma_f32_16x16x32_bf16 v[112:115], v[180:183], v[224:227], v[112:115]
	v_mfma_f32_16x16x32_bf16 v[120:123], v[212:215], v[224:227], v[120:123]
	v_mfma_f32_16x16x32_bf16 v[96:99], v[216:219], v[224:227], v[96:99]
	v_mfma_f32_16x16x32_bf16 v[104:107], v[220:223], v[224:227], v[104:107]
	ds_read_b128 v[224:227], v136 offset:8192
	v_mfma_f32_16x16x32_bf16 v[116:119], v[180:183], v[228:231], v[116:119]
	v_mfma_f32_16x16x32_bf16 v[124:127], v[212:215], v[228:231], v[124:127]
	v_mfma_f32_16x16x32_bf16 v[100:103], v[216:219], v[228:231], v[100:103]
	v_mfma_f32_16x16x32_bf16 v[108:111], v[220:223], v[228:231], v[108:111]
	ds_read_b128 v[228:231], v136 offset:10240
	v_mfma_f32_16x16x32_bf16 v[80:83], v[180:183], v[232:235], v[80:83]
	v_mfma_f32_16x16x32_bf16 v[88:91], v[212:215], v[232:235], v[88:91]
	v_mfma_f32_16x16x32_bf16 v[64:67], v[216:219], v[232:235], v[64:67]
	v_mfma_f32_16x16x32_bf16 v[72:75], v[220:223], v[232:235], v[72:75]
	ds_read_b128 v[232:235], v136 offset:12288
	v_mfma_f32_16x16x32_bf16 v[84:87], v[180:183], v[236:239], v[84:87]
	v_mfma_f32_16x16x32_bf16 v[92:95], v[212:215], v[236:239], v[92:95]
	v_mfma_f32_16x16x32_bf16 v[68:71], v[216:219], v[236:239], v[68:71]
	v_mfma_f32_16x16x32_bf16 v[76:79], v[220:223], v[236:239], v[76:79]
	ds_read_b128 v[236:239], v136 offset:14336
	s_waitcnt lgkmcnt(3)
	v_mfma_f32_16x16x32_bf16 v[48:51], v[180:183], v[224:227], v[48:51]
	v_mfma_f32_16x16x32_bf16 v[56:59], v[212:215], v[224:227], v[56:59]
	v_mfma_f32_16x16x32_bf16 v[32:35], v[216:219], v[224:227], v[32:35]
	v_mfma_f32_16x16x32_bf16 v[40:43], v[220:223], v[224:227], v[40:43]
	s_waitcnt lgkmcnt(2)
	v_mfma_f32_16x16x32_bf16 v[52:55], v[180:183], v[228:231], v[52:55]
	v_mfma_f32_16x16x32_bf16 v[60:63], v[212:215], v[228:231], v[60:63]
	v_mfma_f32_16x16x32_bf16 v[36:39], v[216:219], v[228:231], v[36:39]
	v_mfma_f32_16x16x32_bf16 v[44:47], v[220:223], v[228:231], v[44:47]
	s_waitcnt lgkmcnt(1)
	v_mfma_f32_16x16x32_bf16 v[16:19], v[180:183], v[232:235], v[16:19]
	v_mfma_f32_16x16x32_bf16 v[24:27], v[212:215], v[232:235], v[24:27]
	v_mfma_f32_16x16x32_bf16 v[0:3], v[216:219], v[232:235], v[0:3]
	v_mfma_f32_16x16x32_bf16 v[8:11], v[220:223], v[232:235], v[8:11]
	s_waitcnt lgkmcnt(0)
	s_waitcnt vmcnt(0)
	s_barrier
	v_mfma_f32_16x16x32_bf16 v[20:23], v[180:183], v[236:239], v[20:23]
	v_mfma_f32_16x16x32_bf16 v[28:31], v[212:215], v[236:239], v[28:31]
	v_mfma_f32_16x16x32_bf16 v[4:7], v[216:219], v[236:239], v[4:7]
	v_mfma_f32_16x16x32_bf16 v[12:15], v[220:223], v[236:239], v[12:15]
	s_nop 15
	v_permlane16_swap_b32_e32 v112, v116
	v_permlane16_swap_b32_e32 v113, v117
	v_permlane16_swap_b32_e32 v114, v118
	v_permlane16_swap_b32_e32 v115, v119
	v_permlane16_swap_b32_e32 v120, v124
	v_permlane16_swap_b32_e32 v121, v125
	v_permlane16_swap_b32_e32 v122, v126
	v_permlane16_swap_b32_e32 v123, v127
	v_permlane16_swap_b32_e32 v96, v100
	v_permlane16_swap_b32_e32 v97, v101
	v_permlane16_swap_b32_e32 v98, v102
	v_permlane16_swap_b32_e32 v99, v103
	v_permlane16_swap_b32_e32 v104, v108
	v_permlane16_swap_b32_e32 v105, v109
	v_permlane16_swap_b32_e32 v106, v110
	v_permlane16_swap_b32_e32 v107, v111
	v_permlane16_swap_b32_e32 v80, v84
	v_permlane16_swap_b32_e32 v81, v85
	v_permlane16_swap_b32_e32 v82, v86
	v_permlane16_swap_b32_e32 v83, v87
	v_permlane16_swap_b32_e32 v88, v92
	v_permlane16_swap_b32_e32 v89, v93
	v_permlane16_swap_b32_e32 v90, v94
	v_permlane16_swap_b32_e32 v91, v95
	v_permlane16_swap_b32_e32 v64, v68
	v_permlane16_swap_b32_e32 v65, v69
	v_permlane16_swap_b32_e32 v66, v70
	v_permlane16_swap_b32_e32 v67, v71
	v_permlane16_swap_b32_e32 v72, v76
	v_permlane16_swap_b32_e32 v73, v77
	v_permlane16_swap_b32_e32 v74, v78
	v_permlane16_swap_b32_e32 v75, v79
	v_permlane16_swap_b32_e32 v48, v52
	v_permlane16_swap_b32_e32 v49, v53
	v_permlane16_swap_b32_e32 v50, v54
	v_permlane16_swap_b32_e32 v51, v55
	v_permlane16_swap_b32_e32 v56, v60
	v_permlane16_swap_b32_e32 v57, v61
	v_permlane16_swap_b32_e32 v58, v62
	v_permlane16_swap_b32_e32 v59, v63
	v_permlane16_swap_b32_e32 v32, v36
	v_permlane16_swap_b32_e32 v33, v37
	v_permlane16_swap_b32_e32 v34, v38
	v_permlane16_swap_b32_e32 v35, v39
	v_permlane16_swap_b32_e32 v40, v44
	v_permlane16_swap_b32_e32 v41, v45
	v_permlane16_swap_b32_e32 v42, v46
	v_permlane16_swap_b32_e32 v43, v47
	v_permlane16_swap_b32_e32 v16, v20
	v_permlane16_swap_b32_e32 v17, v21
	v_permlane16_swap_b32_e32 v18, v22
	v_permlane16_swap_b32_e32 v19, v23
	v_permlane16_swap_b32_e32 v24, v28
	v_permlane16_swap_b32_e32 v25, v29
	v_permlane16_swap_b32_e32 v26, v30
	v_permlane16_swap_b32_e32 v27, v31
	v_permlane16_swap_b32_e32 v0, v4
	v_permlane16_swap_b32_e32 v1, v5
	v_permlane16_swap_b32_e32 v2, v6
	v_permlane16_swap_b32_e32 v3, v7
	v_permlane16_swap_b32_e32 v8, v12
	v_permlane16_swap_b32_e32 v9, v13
	v_permlane16_swap_b32_e32 v10, v14
	v_permlane16_swap_b32_e32 v11, v15
	v_permlane32_swap_b32_e32 v112, v116
	v_permlane32_swap_b32_e32 v113, v117
	v_permlane32_swap_b32_e32 v114, v118
	v_permlane32_swap_b32_e32 v115, v119
	v_permlane32_swap_b32_e32 v120, v124
	v_permlane32_swap_b32_e32 v121, v125
	v_permlane32_swap_b32_e32 v122, v126
	v_permlane32_swap_b32_e32 v123, v127
	v_permlane32_swap_b32_e32 v96, v100
	v_permlane32_swap_b32_e32 v97, v101
	v_permlane32_swap_b32_e32 v98, v102
	v_permlane32_swap_b32_e32 v99, v103
	v_permlane32_swap_b32_e32 v104, v108
	v_permlane32_swap_b32_e32 v105, v109
	v_permlane32_swap_b32_e32 v106, v110
	v_permlane32_swap_b32_e32 v107, v111
	v_permlane32_swap_b32_e32 v80, v84
	v_permlane32_swap_b32_e32 v81, v85
	v_permlane32_swap_b32_e32 v82, v86
	v_permlane32_swap_b32_e32 v83, v87
	v_permlane32_swap_b32_e32 v88, v92
	v_permlane32_swap_b32_e32 v89, v93
	v_permlane32_swap_b32_e32 v90, v94
	v_permlane32_swap_b32_e32 v91, v95
	v_permlane32_swap_b32_e32 v64, v68
	v_permlane32_swap_b32_e32 v65, v69
	v_permlane32_swap_b32_e32 v66, v70
	v_permlane32_swap_b32_e32 v67, v71
	v_permlane32_swap_b32_e32 v72, v76
	v_permlane32_swap_b32_e32 v73, v77
	v_permlane32_swap_b32_e32 v74, v78
	v_permlane32_swap_b32_e32 v75, v79
	v_permlane32_swap_b32_e32 v48, v52
	v_permlane32_swap_b32_e32 v49, v53
	v_permlane32_swap_b32_e32 v50, v54
	v_permlane32_swap_b32_e32 v51, v55
	v_permlane32_swap_b32_e32 v56, v60
	v_permlane32_swap_b32_e32 v57, v61
	v_permlane32_swap_b32_e32 v58, v62
	v_permlane32_swap_b32_e32 v59, v63
	v_permlane32_swap_b32_e32 v32, v36
	v_permlane32_swap_b32_e32 v33, v37
	v_permlane32_swap_b32_e32 v34, v38
	v_permlane32_swap_b32_e32 v35, v39
	v_permlane32_swap_b32_e32 v40, v44
	v_permlane32_swap_b32_e32 v41, v45
	v_permlane32_swap_b32_e32 v42, v46
	v_permlane32_swap_b32_e32 v43, v47
	v_permlane32_swap_b32_e32 v16, v20
	v_permlane32_swap_b32_e32 v17, v21
	v_permlane32_swap_b32_e32 v18, v22
	v_permlane32_swap_b32_e32 v19, v23
	v_permlane32_swap_b32_e32 v24, v28
	v_permlane32_swap_b32_e32 v25, v29
	v_permlane32_swap_b32_e32 v26, v30
	v_permlane32_swap_b32_e32 v27, v31
	v_permlane32_swap_b32_e32 v0, v4
	v_permlane32_swap_b32_e32 v1, v5
	v_permlane32_swap_b32_e32 v2, v6
	v_permlane32_swap_b32_e32 v3, v7
	v_permlane32_swap_b32_e32 v8, v12
	v_permlane32_swap_b32_e32 v9, v13
	v_permlane32_swap_b32_e32 v10, v14
	v_permlane32_swap_b32_e32 v11, v15
	s_nop 1

.Lg162_loop:
	s_add_u32 s51, s50, 0x10000
	s_sub_u32 s53, s51, 0x28000
	s_cmp_ge_u32 s51, 0x28000
	s_cselect_b32 s51, s53, s51
	s_add_u32 s52, s49, 0x20000
	s_sub_u32 s53, s52, 0x28000
	s_cmp_ge_u32 s52, 0x28000
	s_cselect_b32 s52, s53, s52
	v_add_u32_e32 v167, s50, v145
	s_waitcnt lgkmcnt(4)
	s_waitcnt lgkmcnt(3)
	v_mfma_f32_16x16x32_bf16 v[112:115], v[188:191], v[220:223], v[112:115]
	v_mfma_f32_16x16x32_bf16 v[120:123], v[192:195], v[220:223], v[120:123]
	v_mfma_f32_16x16x32_bf16 v[96:99], v[196:199], v[220:223], v[96:99]
	v_mfma_f32_16x16x32_bf16 v[104:107], v[200:203], v[220:223], v[104:107]
	s_add_u32 m0, s51, s48
	s_nop 0
	global_load_lds_dwordx4 v169, s[64:65]
	s_add_u32 s64, s64, 0x80
	s_addc_u32 s65, s65, 0
	s_add_u32 s53, s51, s48
	s_add_u32 m0, s53, 0x2000
	s_nop 0
	global_load_lds_dwordx4 v169, s[66:67]
	s_add_u32 s66, s66, 0x80
	s_addc_u32 s67, s67, 0
	ds_read_b128 v[220:223], v166 offset:8192
	s_waitcnt lgkmcnt(3)
	v_mfma_f32_16x16x32_bf16 v[116:119], v[188:191], v[224:227], v[116:119]
	v_mfma_f32_16x16x32_bf16 v[124:127], v[192:195], v[224:227], v[124:127]
	v_mfma_f32_16x16x32_bf16 v[100:103], v[196:199], v[224:227], v[100:103]
	v_mfma_f32_16x16x32_bf16 v[108:111], v[200:203], v[224:227], v[108:111]
	s_add_u32 s53, s51, s48
	s_add_u32 m0, s53, 0x4000
	s_nop 0
	global_load_lds_dwordx4 v169, s[68:69]
	s_add_u32 s68, s68, 0x80
	s_addc_u32 s69, s69, 0
	s_add_u32 s53, s51, s48
	s_add_u32 m0, s53, 0x6000
	s_nop 0
	global_load_lds_dwordx4 v169, s[70:71]
	s_add_u32 s70, s70, 0x80
	s_addc_u32 s71, s71, 0
	ds_read_b128 v[224:227], v166 offset:10240
	s_waitcnt lgkmcnt(3)
	v_mfma_f32_16x16x32_bf16 v[80:83], v[188:191], v[228:231], v[80:83]
	v_mfma_f32_16x16x32_bf16 v[88:91], v[192:195], v[228:231], v[88:91]
	v_mfma_f32_16x16x32_bf16 v[64:67], v[196:199], v[228:231], v[64:67]
	v_mfma_f32_16x16x32_bf16 v[72:75], v[200:203], v[228:231], v[72:75]
	ds_read_b128 v[228:231], v166 offset:12288
	s_waitcnt lgkmcnt(3)
	v_mfma_f32_16x16x32_bf16 v[84:87], v[188:191], v[232:235], v[84:87]
	v_mfma_f32_16x16x32_bf16 v[92:95], v[192:195], v[232:235], v[92:95]
	v_mfma_f32_16x16x32_bf16 v[68:71], v[196:199], v[232:235], v[68:71]
	v_mfma_f32_16x16x32_bf16 v[76:79], v[200:203], v[232:235], v[76:79]
	ds_read_b128 v[232:235], v166 offset:14336
	v_add_u32_e32 v166, s49, v143
	s_waitcnt lgkmcnt(3)
	v_mfma_f32_16x16x32_bf16 v[48:51], v[188:191], v[220:223], v[48:51]
	v_mfma_f32_16x16x32_bf16 v[56:59], v[192:195], v[220:223], v[56:59]
	v_mfma_f32_16x16x32_bf16 v[32:35], v[196:199], v[220:223], v[32:35]
	v_mfma_f32_16x16x32_bf16 v[40:43], v[200:203], v[220:223], v[40:43]
	ds_read_b128 v[220:223], v166
	ds_read_b128 v[204:207], v167
	s_waitcnt lgkmcnt(4)
	v_mfma_f32_16x16x32_bf16 v[52:55], v[188:191], v[224:227], v[52:55]
	v_mfma_f32_16x16x32_bf16 v[60:63], v[192:195], v[224:227], v[60:63]
	v_mfma_f32_16x16x32_bf16 v[36:39], v[196:199], v[224:227], v[36:39]
	v_mfma_f32_16x16x32_bf16 v[44:47], v[200:203], v[224:227], v[44:47]
	ds_read_b128 v[224:227], v166 offset:2048
	ds_read_b128 v[208:211], v167 offset:2048
	s_waitcnt lgkmcnt(5)
	v_mfma_f32_16x16x32_bf16 v[16:19], v[188:191], v[228:231], v[16:19]
	v_mfma_f32_16x16x32_bf16 v[24:27], v[192:195], v[228:231], v[24:27]
	v_mfma_f32_16x16x32_bf16 v[0:3], v[196:199], v[228:231], v[0:3]
	v_mfma_f32_16x16x32_bf16 v[8:11], v[200:203], v[228:231], v[8:11]
	ds_read_b128 v[228:231], v166 offset:4096
	ds_read_b128 v[212:215], v167 offset:4096
	s_waitcnt lgkmcnt(6)
	v_mfma_f32_16x16x32_bf16 v[20:23], v[188:191], v[232:235], v[20:23]
	v_mfma_f32_16x16x32_bf16 v[28:31], v[192:195], v[232:235], v[28:31]
	v_mfma_f32_16x16x32_bf16 v[4:7], v[196:199], v[232:235], v[4:7]
	v_mfma_f32_16x16x32_bf16 v[12:15], v[200:203], v[232:235], v[12:15]
	ds_read_b128 v[232:235], v166 offset:6144
	ds_read_b128 v[216:219], v167 offset:6144
	s_waitcnt lgkmcnt(0)
	v_mfma_f32_16x16x32_bf16 v[112:115], v[204:207], v[220:223], v[112:115]
	v_mfma_f32_16x16x32_bf16 v[120:123], v[208:211], v[220:223], v[120:123]
	v_mfma_f32_16x16x32_bf16 v[96:99], v[212:215], v[220:223], v[96:99]
	v_mfma_f32_16x16x32_bf16 v[104:107], v[216:219], v[220:223], v[104:107]
	ds_read_b128 v[220:223], v166 offset:8192
	v_mfma_f32_16x16x32_bf16 v[116:119], v[204:207], v[224:227], v[116:119]
	v_mfma_f32_16x16x32_bf16 v[124:127], v[208:211], v[224:227], v[124:127]
	v_mfma_f32_16x16x32_bf16 v[100:103], v[212:215], v[224:227], v[100:103]
	v_mfma_f32_16x16x32_bf16 v[108:111], v[216:219], v[224:227], v[108:111]
	ds_read_b128 v[224:227], v166 offset:10240
	v_mfma_f32_16x16x32_bf16 v[80:83], v[204:207], v[228:231], v[80:83]
	v_mfma_f32_16x16x32_bf16 v[88:91], v[208:211], v[228:231], v[88:91]
	v_mfma_f32_16x16x32_bf16 v[64:67], v[212:215], v[228:231], v[64:67]
	v_mfma_f32_16x16x32_bf16 v[72:75], v[216:219], v[228:231], v[72:75]
	ds_read_b128 v[228:231], v166 offset:12288
	v_mfma_f32_16x16x32_bf16 v[84:87], v[204:207], v[232:235], v[84:87]
	v_mfma_f32_16x16x32_bf16 v[92:95], v[208:211], v[232:235], v[92:95]
	v_mfma_f32_16x16x32_bf16 v[68:71], v[212:215], v[232:235], v[68:71]
	v_mfma_f32_16x16x32_bf16 v[76:79], v[216:219], v[232:235], v[76:79]
	ds_read_b128 v[232:235], v166 offset:14336
	s_waitcnt lgkmcnt(3)
	v_mfma_f32_16x16x32_bf16 v[48:51], v[204:207], v[220:223], v[48:51]
	v_mfma_f32_16x16x32_bf16 v[56:59], v[208:211], v[220:223], v[56:59]
	v_mfma_f32_16x16x32_bf16 v[32:35], v[212:215], v[220:223], v[32:35]
	v_mfma_f32_16x16x32_bf16 v[40:43], v[216:219], v[220:223], v[40:43]
	s_add_u32 m0, s52, s48
	s_nop 0
	global_load_lds_dwordx4 v168, s[56:57]
	s_add_u32 s56, s56, 0x80
	s_addc_u32 s57, s57, 0
	s_add_u32 s53, s52, s48
	s_add_u32 m0, s53, 0x2000
	s_nop 0
	global_load_lds_dwordx4 v168, s[58:59]
	s_add_u32 s58, s58, 0x80
	s_addc_u32 s59, s59, 0
	s_waitcnt lgkmcnt(2)
	v_mfma_f32_16x16x32_bf16 v[52:55], v[204:207], v[224:227], v[52:55]
	v_mfma_f32_16x16x32_bf16 v[60:63], v[208:211], v[224:227], v[60:63]
	v_mfma_f32_16x16x32_bf16 v[36:39], v[212:215], v[224:227], v[36:39]
	v_mfma_f32_16x16x32_bf16 v[44:47], v[216:219], v[224:227], v[44:47]
	s_add_u32 s53, s52, s48
	s_add_u32 m0, s53, 0x4000
	s_nop 0
	global_load_lds_dwordx4 v168, s[60:61]
	s_add_u32 s60, s60, 0x80
	s_addc_u32 s61, s61, 0
	s_add_u32 s53, s52, s48
	s_add_u32 m0, s53, 0x6000
	s_nop 0
	global_load_lds_dwordx4 v168, s[62:63]
	s_add_u32 s62, s62, 0x80
	s_addc_u32 s63, s63, 0
	s_waitcnt lgkmcnt(1)
	v_mfma_f32_16x16x32_bf16 v[16:19], v[204:207], v[228:231], v[16:19]
	v_mfma_f32_16x16x32_bf16 v[24:27], v[208:211], v[228:231], v[24:27]
	v_mfma_f32_16x16x32_bf16 v[0:3], v[212:215], v[228:231], v[0:3]
	v_mfma_f32_16x16x32_bf16 v[8:11], v[216:219], v[228:231], v[8:11]
	s_waitcnt lgkmcnt(0)
	s_add_u32 s28, s28, 0x80
	s_addc_u32 s29, s29, 0
	s_add_u32 s49, s49, 0x10000
	s_sub_u32 s53, s49, 0x28000
	s_cmp_ge_u32 s49, 0x28000
	s_cselect_b32 s49, s53, s49
	s_mov_b32 s50, s51
	s_waitcnt vmcnt(4)
	s_barrier
	v_add_u32_e32 v167, s50, v144
	v_add_u32_e32 v166, s49, v142
	ds_read_b128 v[188:191], v167
	ds_read_b128 v[192:195], v167 offset:2048
	ds_read_b128 v[196:199], v167 offset:4096
	ds_read_b128 v[200:203], v167 offset:6144
	ds_read_b128 v[220:223], v166
	ds_read_b128 v[224:227], v166 offset:2048
	ds_read_b128 v[228:231], v166 offset:4096
	v_mfma_f32_16x16x32_bf16 v[20:23], v[204:207], v[232:235], v[20:23]
	v_mfma_f32_16x16x32_bf16 v[28:31], v[208:211], v[232:235], v[28:31]
	v_mfma_f32_16x16x32_bf16 v[4:7], v[212:215], v[232:235], v[4:7]
	v_mfma_f32_16x16x32_bf16 v[12:15], v[216:219], v[232:235], v[12:15]
	ds_read_b128 v[232:235], v166 offset:6144
	s_cmpk_lg_i32 s28, 0xf00
	s_cbranch_scc1 .Lg162_loop
	s_add_u32 s51, s50, 0x10000
	s_sub_u32 s53, s51, 0x28000
	s_cmp_ge_u32 s51, 0x28000
	s_cselect_b32 s51, s53, s51
	v_add_u32_e32 v167, s50, v145
	s_waitcnt lgkmcnt(4)
	s_waitcnt lgkmcnt(3)
	v_mfma_f32_16x16x32_bf16 v[112:115], v[188:191], v[220:223], v[112:115]
	v_mfma_f32_16x16x32_bf16 v[120:123], v[192:195], v[220:223], v[120:123]
	v_mfma_f32_16x16x32_bf16 v[96:99], v[196:199], v[220:223], v[96:99]
	v_mfma_f32_16x16x32_bf16 v[104:107], v[200:203], v[220:223], v[104:107]
	s_add_u32 m0, s51, s48
	s_nop 0
	global_load_lds_dwordx4 v169, s[64:65]
	s_add_u32 s64, s64, 0x80
	s_addc_u32 s65, s65, 0
	s_add_u32 s53, s51, s48
	s_add_u32 m0, s53, 0x2000
	s_nop 0
	global_load_lds_dwordx4 v169, s[66:67]
	s_add_u32 s66, s66, 0x80
	s_addc_u32 s67, s67, 0
	ds_read_b128 v[220:223], v166 offset:8192
	s_waitcnt lgkmcnt(3)
	v_mfma_f32_16x16x32_bf16 v[116:119], v[188:191], v[224:227], v[116:119]
	v_mfma_f32_16x16x32_bf16 v[124:127], v[192:195], v[224:227], v[124:127]
	v_mfma_f32_16x16x32_bf16 v[100:103], v[196:199], v[224:227], v[100:103]
	v_mfma_f32_16x16x32_bf16 v[108:111], v[200:203], v[224:227], v[108:111]
	s_add_u32 s53, s51, s48
	s_add_u32 m0, s53, 0x4000
	s_nop 0
	global_load_lds_dwordx4 v169, s[68:69]
	s_add_u32 s68, s68, 0x80
	s_addc_u32 s69, s69, 0
	s_add_u32 s53, s51, s48
	s_add_u32 m0, s53, 0x6000
	s_nop 0
	global_load_lds_dwordx4 v169, s[70:71]
	s_add_u32 s70, s70, 0x80
	s_addc_u32 s71, s71, 0
	ds_read_b128 v[224:227], v166 offset:10240
	s_waitcnt lgkmcnt(3)
	v_mfma_f32_16x16x32_bf16 v[80:83], v[188:191], v[228:231], v[80:83]
	v_mfma_f32_16x16x32_bf16 v[88:91], v[192:195], v[228:231], v[88:91]
	v_mfma_f32_16x16x32_bf16 v[64:67], v[196:199], v[228:231], v[64:67]
	v_mfma_f32_16x16x32_bf16 v[72:75], v[200:203], v[228:231], v[72:75]
	ds_read_b128 v[228:231], v166 offset:12288
	s_waitcnt lgkmcnt(3)
	v_mfma_f32_16x16x32_bf16 v[84:87], v[188:191], v[232:235], v[84:87]
	v_mfma_f32_16x16x32_bf16 v[92:95], v[192:195], v[232:235], v[92:95]
	v_mfma_f32_16x16x32_bf16 v[68:71], v[196:199], v[232:235], v[68:71]
	v_mfma_f32_16x16x32_bf16 v[76:79], v[200:203], v[232:235], v[76:79]
	ds_read_b128 v[232:235], v166 offset:14336
	v_add_u32_e32 v166, s49, v143
	s_waitcnt lgkmcnt(3)
	v_mfma_f32_16x16x32_bf16 v[48:51], v[188:191], v[220:223], v[48:51]
	v_mfma_f32_16x16x32_bf16 v[56:59], v[192:195], v[220:223], v[56:59]
	v_mfma_f32_16x16x32_bf16 v[32:35], v[196:199], v[220:223], v[32:35]
	v_mfma_f32_16x16x32_bf16 v[40:43], v[200:203], v[220:223], v[40:43]
	ds_read_b128 v[220:223], v166
	ds_read_b128 v[204:207], v167
	s_waitcnt lgkmcnt(4)
	v_mfma_f32_16x16x32_bf16 v[52:55], v[188:191], v[224:227], v[52:55]
	v_mfma_f32_16x16x32_bf16 v[60:63], v[192:195], v[224:227], v[60:63]
	v_mfma_f32_16x16x32_bf16 v[36:39], v[196:199], v[224:227], v[36:39]
	v_mfma_f32_16x16x32_bf16 v[44:47], v[200:203], v[224:227], v[44:47]
	ds_read_b128 v[224:227], v166 offset:2048
	ds_read_b128 v[208:211], v167 offset:2048
	s_waitcnt lgkmcnt(5)
	v_mfma_f32_16x16x32_bf16 v[16:19], v[188:191], v[228:231], v[16:19]
	v_mfma_f32_16x16x32_bf16 v[24:27], v[192:195], v[228:231], v[24:27]
	v_mfma_f32_16x16x32_bf16 v[0:3], v[196:199], v[228:231], v[0:3]
	v_mfma_f32_16x16x32_bf16 v[8:11], v[200:203], v[228:231], v[8:11]
	ds_read_b128 v[228:231], v166 offset:4096
	ds_read_b128 v[212:215], v167 offset:4096
	s_waitcnt lgkmcnt(6)
	v_mfma_f32_16x16x32_bf16 v[20:23], v[188:191], v[232:235], v[20:23]
	v_mfma_f32_16x16x32_bf16 v[28:31], v[192:195], v[232:235], v[28:31]
	v_mfma_f32_16x16x32_bf16 v[4:7], v[196:199], v[232:235], v[4:7]
	v_mfma_f32_16x16x32_bf16 v[12:15], v[200:203], v[232:235], v[12:15]
	ds_read_b128 v[232:235], v166 offset:6144
	ds_read_b128 v[216:219], v167 offset:6144
	s_waitcnt lgkmcnt(0)
	v_mfma_f32_16x16x32_bf16 v[112:115], v[204:207], v[220:223], v[112:115]
	v_mfma_f32_16x16x32_bf16 v[120:123], v[208:211], v[220:223], v[120:123]
	v_mfma_f32_16x16x32_bf16 v[96:99], v[212:215], v[220:223], v[96:99]
	v_mfma_f32_16x16x32_bf16 v[104:107], v[216:219], v[220:223], v[104:107]
	ds_read_b128 v[220:223], v166 offset:8192
	v_mfma_f32_16x16x32_bf16 v[116:119], v[204:207], v[224:227], v[116:119]
	v_mfma_f32_16x16x32_bf16 v[124:127], v[208:211], v[224:227], v[124:127]
	v_mfma_f32_16x16x32_bf16 v[100:103], v[212:215], v[224:227], v[100:103]
	v_mfma_f32_16x16x32_bf16 v[108:111], v[216:219], v[224:227], v[108:111]
	ds_read_b128 v[224:227], v166 offset:10240
	v_mfma_f32_16x16x32_bf16 v[80:83], v[204:207], v[228:231], v[80:83]
	v_mfma_f32_16x16x32_bf16 v[88:91], v[208:211], v[228:231], v[88:91]
	v_mfma_f32_16x16x32_bf16 v[64:67], v[212:215], v[228:231], v[64:67]
	v_mfma_f32_16x16x32_bf16 v[72:75], v[216:219], v[228:231], v[72:75]
	ds_read_b128 v[228:231], v166 offset:12288
	v_mfma_f32_16x16x32_bf16 v[84:87], v[204:207], v[232:235], v[84:87]
	v_mfma_f32_16x16x32_bf16 v[92:95], v[208:211], v[232:235], v[92:95]
	v_mfma_f32_16x16x32_bf16 v[68:71], v[212:215], v[232:235], v[68:71]
	v_mfma_f32_16x16x32_bf16 v[76:79], v[216:219], v[232:235], v[76:79]
	ds_read_b128 v[232:235], v166 offset:14336
	s_waitcnt lgkmcnt(3)
	v_mfma_f32_16x16x32_bf16 v[48:51], v[204:207], v[220:223], v[48:51]
	v_mfma_f32_16x16x32_bf16 v[56:59], v[208:211], v[220:223], v[56:59]
	v_mfma_f32_16x16x32_bf16 v[32:35], v[212:215], v[220:223], v[32:35]
	v_mfma_f32_16x16x32_bf16 v[40:43], v[216:219], v[220:223], v[40:43]
	s_waitcnt lgkmcnt(2)
	v_mfma_f32_16x16x32_bf16 v[52:55], v[204:207], v[224:227], v[52:55]
	v_mfma_f32_16x16x32_bf16 v[60:63], v[208:211], v[224:227], v[60:63]
	v_mfma_f32_16x16x32_bf16 v[36:39], v[212:215], v[224:227], v[36:39]
	v_mfma_f32_16x16x32_bf16 v[44:47], v[216:219], v[224:227], v[44:47]
	s_waitcnt lgkmcnt(1)
	v_mfma_f32_16x16x32_bf16 v[16:19], v[204:207], v[228:231], v[16:19]
	v_mfma_f32_16x16x32_bf16 v[24:27], v[208:211], v[228:231], v[24:27]
	v_mfma_f32_16x16x32_bf16 v[0:3], v[212:215], v[228:231], v[0:3]
	v_mfma_f32_16x16x32_bf16 v[8:11], v[216:219], v[228:231], v[8:11]
	s_waitcnt lgkmcnt(0)
	s_add_u32 s28, s28, 0x80
	s_addc_u32 s29, s29, 0
	s_add_u32 s49, s49, 0x10000
	s_sub_u32 s53, s49, 0x28000
	s_cmp_ge_u32 s49, 0x28000
	s_cselect_b32 s49, s53, s49
	s_mov_b32 s50, s51
	s_waitcnt vmcnt(0)
	s_barrier
	v_add_u32_e32 v167, s50, v144
	v_add_u32_e32 v166, s49, v142
	ds_read_b128 v[188:191], v167
	ds_read_b128 v[192:195], v167 offset:2048
	ds_read_b128 v[196:199], v167 offset:4096
	ds_read_b128 v[200:203], v167 offset:6144
	ds_read_b128 v[220:223], v166
	ds_read_b128 v[224:227], v166 offset:2048
	ds_read_b128 v[228:231], v166 offset:4096
	v_mfma_f32_16x16x32_bf16 v[20:23], v[204:207], v[232:235], v[20:23]
	v_mfma_f32_16x16x32_bf16 v[28:31], v[208:211], v[232:235], v[28:31]
	v_mfma_f32_16x16x32_bf16 v[4:7], v[212:215], v[232:235], v[4:7]
	v_mfma_f32_16x16x32_bf16 v[12:15], v[216:219], v[232:235], v[12:15]
	ds_read_b128 v[232:235], v166 offset:6144
	v_add_u32_e32 v167, s50, v145
	s_waitcnt lgkmcnt(4)
	s_waitcnt lgkmcnt(3)
	v_mfma_f32_16x16x32_bf16 v[112:115], v[188:191], v[220:223], v[112:115]
	v_mfma_f32_16x16x32_bf16 v[120:123], v[192:195], v[220:223], v[120:123]
	v_mfma_f32_16x16x32_bf16 v[96:99], v[196:199], v[220:223], v[96:99]
	v_mfma_f32_16x16x32_bf16 v[104:107], v[200:203], v[220:223], v[104:107]
	ds_read_b128 v[220:223], v166 offset:8192
	s_waitcnt lgkmcnt(3)
	v_mfma_f32_16x16x32_bf16 v[116:119], v[188:191], v[224:227], v[116:119]
	v_mfma_f32_16x16x32_bf16 v[124:127], v[192:195], v[224:227], v[124:127]
	v_mfma_f32_16x16x32_bf16 v[100:103], v[196:199], v[224:227], v[100:103]
	v_mfma_f32_16x16x32_bf16 v[108:111], v[200:203], v[224:227], v[108:111]
	ds_read_b128 v[224:227], v166 offset:10240
	s_waitcnt lgkmcnt(3)
	v_mfma_f32_16x16x32_bf16 v[80:83], v[188:191], v[228:231], v[80:83]
	v_mfma_f32_16x16x32_bf16 v[88:91], v[192:195], v[228:231], v[88:91]
	v_mfma_f32_16x16x32_bf16 v[64:67], v[196:199], v[228:231], v[64:67]
	v_mfma_f32_16x16x32_bf16 v[72:75], v[200:203], v[228:231], v[72:75]
	ds_read_b128 v[228:231], v166 offset:12288
	s_waitcnt lgkmcnt(3)
	v_mfma_f32_16x16x32_bf16 v[84:87], v[188:191], v[232:235], v[84:87]
	v_mfma_f32_16x16x32_bf16 v[92:95], v[192:195], v[232:235], v[92:95]
	v_mfma_f32_16x16x32_bf16 v[68:71], v[196:199], v[232:235], v[68:71]
	v_mfma_f32_16x16x32_bf16 v[76:79], v[200:203], v[232:235], v[76:79]
	ds_read_b128 v[232:235], v166 offset:14336
	v_add_u32_e32 v166, s49, v143
	s_waitcnt lgkmcnt(3)
	v_mfma_f32_16x16x32_bf16 v[48:51], v[188:191], v[220:223], v[48:51]
	v_mfma_f32_16x16x32_bf16 v[56:59], v[192:195], v[220:223], v[56:59]
	v_mfma_f32_16x16x32_bf16 v[32:35], v[196:199], v[220:223], v[32:35]
	v_mfma_f32_16x16x32_bf16 v[40:43], v[200:203], v[220:223], v[40:43]
	ds_read_b128 v[220:223], v166
	ds_read_b128 v[204:207], v167
	s_waitcnt lgkmcnt(4)
	v_mfma_f32_16x16x32_bf16 v[52:55], v[188:191], v[224:227], v[52:55]
	v_mfma_f32_16x16x32_bf16 v[60:63], v[192:195], v[224:227], v[60:63]
	v_mfma_f32_16x16x32_bf16 v[36:39], v[196:199], v[224:227], v[36:39]
	v_mfma_f32_16x16x32_bf16 v[44:47], v[200:203], v[224:227], v[44:47]
	ds_read_b128 v[224:227], v166 offset:2048
	ds_read_b128 v[208:211], v167 offset:2048
	s_waitcnt lgkmcnt(5)
	v_mfma_f32_16x16x32_bf16 v[16:19], v[188:191], v[228:231], v[16:19]
	v_mfma_f32_16x16x32_bf16 v[24:27], v[192:195], v[228:231], v[24:27]
	v_mfma_f32_16x16x32_bf16 v[0:3], v[196:199], v[228:231], v[0:3]
	v_mfma_f32_16x16x32_bf16 v[8:11], v[200:203], v[228:231], v[8:11]
	ds_read_b128 v[228:231], v166 offset:4096
	ds_read_b128 v[212:215], v167 offset:4096
	s_waitcnt lgkmcnt(6)
	v_mfma_f32_16x16x32_bf16 v[20:23], v[188:191], v[232:235], v[20:23]
	v_mfma_f32_16x16x32_bf16 v[28:31], v[192:195], v[232:235], v[28:31]
	v_mfma_f32_16x16x32_bf16 v[4:7], v[196:199], v[232:235], v[4:7]
	v_mfma_f32_16x16x32_bf16 v[12:15], v[200:203], v[232:235], v[12:15]
	ds_read_b128 v[232:235], v166 offset:6144
	ds_read_b128 v[216:219], v167 offset:6144
	s_waitcnt lgkmcnt(0)
	v_mfma_f32_16x16x32_bf16 v[112:115], v[204:207], v[220:223], v[112:115]
	v_mfma_f32_16x16x32_bf16 v[120:123], v[208:211], v[220:223], v[120:123]
	v_mfma_f32_16x16x32_bf16 v[96:99], v[212:215], v[220:223], v[96:99]
	v_mfma_f32_16x16x32_bf16 v[104:107], v[216:219], v[220:223], v[104:107]
	ds_read_b128 v[220:223], v166 offset:8192
	v_mfma_f32_16x16x32_bf16 v[116:119], v[204:207], v[224:227], v[116:119]
	v_mfma_f32_16x16x32_bf16 v[124:127], v[208:211], v[224:227], v[124:127]
	v_mfma_f32_16x16x32_bf16 v[100:103], v[212:215], v[224:227], v[100:103]
	v_mfma_f32_16x16x32_bf16 v[108:111], v[216:219], v[224:227], v[108:111]
	ds_read_b128 v[224:227], v166 offset:10240
	v_mfma_f32_16x16x32_bf16 v[80:83], v[204:207], v[228:231], v[80:83]
	v_mfma_f32_16x16x32_bf16 v[88:91], v[208:211], v[228:231], v[88:91]
	v_mfma_f32_16x16x32_bf16 v[64:67], v[212:215], v[228:231], v[64:67]
	v_mfma_f32_16x16x32_bf16 v[72:75], v[216:219], v[228:231], v[72:75]
	ds_read_b128 v[228:231], v166 offset:12288
	v_mfma_f32_16x16x32_bf16 v[84:87], v[204:207], v[232:235], v[84:87]
	v_mfma_f32_16x16x32_bf16 v[92:95], v[208:211], v[232:235], v[92:95]
	v_mfma_f32_16x16x32_bf16 v[68:71], v[212:215], v[232:235], v[68:71]
	v_mfma_f32_16x16x32_bf16 v[76:79], v[216:219], v[232:235], v[76:79]
	ds_read_b128 v[232:235], v166 offset:14336
	s_waitcnt lgkmcnt(3)
	v_mfma_f32_16x16x32_bf16 v[48:51], v[204:207], v[220:223], v[48:51]
	v_mfma_f32_16x16x32_bf16 v[56:59], v[208:211], v[220:223], v[56:59]
	v_mfma_f32_16x16x32_bf16 v[32:35], v[212:215], v[220:223], v[32:35]
	v_mfma_f32_16x16x32_bf16 v[40:43], v[216:219], v[220:223], v[40:43]
	s_waitcnt lgkmcnt(2)
	v_mfma_f32_16x16x32_bf16 v[52:55], v[204:207], v[224:227], v[52:55]
	v_mfma_f32_16x16x32_bf16 v[60:63], v[208:211], v[224:227], v[60:63]
	v_mfma_f32_16x16x32_bf16 v[36:39], v[212:215], v[224:227], v[36:39]
	v_mfma_f32_16x16x32_bf16 v[44:47], v[216:219], v[224:227], v[44:47]
	s_waitcnt lgkmcnt(1)
	v_mfma_f32_16x16x32_bf16 v[16:19], v[204:207], v[228:231], v[16:19]
	v_mfma_f32_16x16x32_bf16 v[24:27], v[208:211], v[228:231], v[24:27]
	v_mfma_f32_16x16x32_bf16 v[0:3], v[212:215], v[228:231], v[0:3]
	v_mfma_f32_16x16x32_bf16 v[8:11], v[216:219], v[228:231], v[8:11]
	s_waitcnt lgkmcnt(0)
	s_waitcnt vmcnt(0)
	s_barrier
	v_mfma_f32_16x16x32_bf16 v[20:23], v[204:207], v[232:235], v[20:23]
	v_mfma_f32_16x16x32_bf16 v[28:31], v[208:211], v[232:235], v[28:31]
	v_mfma_f32_16x16x32_bf16 v[4:7], v[212:215], v[232:235], v[4:7]
	v_mfma_f32_16x16x32_bf16 v[12:15], v[216:219], v[232:235], v[12:15]
	s_nop 15
	v_permlane16_swap_b32_e32 v112, v116
	v_permlane16_swap_b32_e32 v113, v117
	v_permlane16_swap_b32_e32 v114, v118
	v_permlane16_swap_b32_e32 v115, v119
	v_permlane16_swap_b32_e32 v120, v124
	v_permlane16_swap_b32_e32 v121, v125
	v_permlane16_swap_b32_e32 v122, v126
	v_permlane16_swap_b32_e32 v123, v127
	v_permlane16_swap_b32_e32 v96, v100
	v_permlane16_swap_b32_e32 v97, v101
	v_permlane16_swap_b32_e32 v98, v102
	v_permlane16_swap_b32_e32 v99, v103
	v_permlane16_swap_b32_e32 v104, v108
	v_permlane16_swap_b32_e32 v105, v109
	v_permlane16_swap_b32_e32 v106, v110
	v_permlane16_swap_b32_e32 v107, v111
	v_permlane16_swap_b32_e32 v80, v84
	v_permlane16_swap_b32_e32 v81, v85
	v_permlane16_swap_b32_e32 v82, v86
	v_permlane16_swap_b32_e32 v83, v87
	v_permlane16_swap_b32_e32 v88, v92
	v_permlane16_swap_b32_e32 v89, v93
	v_permlane16_swap_b32_e32 v90, v94
	v_permlane16_swap_b32_e32 v91, v95
	v_permlane16_swap_b32_e32 v64, v68
	v_permlane16_swap_b32_e32 v65, v69
	v_permlane16_swap_b32_e32 v66, v70
	v_permlane16_swap_b32_e32 v67, v71
	v_permlane16_swap_b32_e32 v72, v76
	v_permlane16_swap_b32_e32 v73, v77
	v_permlane16_swap_b32_e32 v74, v78
	v_permlane16_swap_b32_e32 v75, v79
	v_permlane16_swap_b32_e32 v48, v52
	v_permlane16_swap_b32_e32 v49, v53
	v_permlane16_swap_b32_e32 v50, v54
	v_permlane16_swap_b32_e32 v51, v55
	v_permlane16_swap_b32_e32 v56, v60
	v_permlane16_swap_b32_e32 v57, v61
	v_permlane16_swap_b32_e32 v58, v62
	v_permlane16_swap_b32_e32 v59, v63
	v_permlane16_swap_b32_e32 v32, v36
	v_permlane16_swap_b32_e32 v33, v37
	v_permlane16_swap_b32_e32 v34, v38
	v_permlane16_swap_b32_e32 v35, v39
	v_permlane16_swap_b32_e32 v40, v44
	v_permlane16_swap_b32_e32 v41, v45
	v_permlane16_swap_b32_e32 v42, v46
	v_permlane16_swap_b32_e32 v43, v47
	v_permlane16_swap_b32_e32 v16, v20
	v_permlane16_swap_b32_e32 v17, v21
	v_permlane16_swap_b32_e32 v18, v22
	v_permlane16_swap_b32_e32 v19, v23
	v_permlane16_swap_b32_e32 v24, v28
	v_permlane16_swap_b32_e32 v25, v29
	v_permlane16_swap_b32_e32 v26, v30
	v_permlane16_swap_b32_e32 v27, v31
	v_permlane16_swap_b32_e32 v0, v4
	v_permlane16_swap_b32_e32 v1, v5
	v_permlane16_swap_b32_e32 v2, v6
	v_permlane16_swap_b32_e32 v3, v7
	v_permlane16_swap_b32_e32 v8, v12
	v_permlane16_swap_b32_e32 v9, v13
	v_permlane16_swap_b32_e32 v10, v14
	v_permlane16_swap_b32_e32 v11, v15
	v_permlane32_swap_b32_e32 v112, v116
	v_permlane32_swap_b32_e32 v113, v117
	v_permlane32_swap_b32_e32 v114, v118
	v_permlane32_swap_b32_e32 v115, v119
	v_permlane32_swap_b32_e32 v120, v124
	v_permlane32_swap_b32_e32 v121, v125
	v_permlane32_swap_b32_e32 v122, v126
	v_permlane32_swap_b32_e32 v123, v127
	v_permlane32_swap_b32_e32 v96, v100
	v_permlane32_swap_b32_e32 v97, v101
	v_permlane32_swap_b32_e32 v98, v102
	v_permlane32_swap_b32_e32 v99, v103
	v_permlane32_swap_b32_e32 v104, v108
	v_permlane32_swap_b32_e32 v105, v109
	v_permlane32_swap_b32_e32 v106, v110
	v_permlane32_swap_b32_e32 v107, v111
	v_permlane32_swap_b32_e32 v80, v84
	v_permlane32_swap_b32_e32 v81, v85
	v_permlane32_swap_b32_e32 v82, v86
	v_permlane32_swap_b32_e32 v83, v87
	v_permlane32_swap_b32_e32 v88, v92
	v_permlane32_swap_b32_e32 v89, v93
	v_permlane32_swap_b32_e32 v90, v94
	v_permlane32_swap_b32_e32 v91, v95
	v_permlane32_swap_b32_e32 v64, v68
	v_permlane32_swap_b32_e32 v65, v69
	v_permlane32_swap_b32_e32 v66, v70
	v_permlane32_swap_b32_e32 v67, v71
	v_permlane32_swap_b32_e32 v72, v76
	v_permlane32_swap_b32_e32 v73, v77
	v_permlane32_swap_b32_e32 v74, v78
	v_permlane32_swap_b32_e32 v75, v79
	v_permlane32_swap_b32_e32 v48, v52
	v_permlane32_swap_b32_e32 v49, v53
	v_permlane32_swap_b32_e32 v50, v54
	v_permlane32_swap_b32_e32 v51, v55
	v_permlane32_swap_b32_e32 v56, v60
	v_permlane32_swap_b32_e32 v57, v61
	v_permlane32_swap_b32_e32 v58, v62
	v_permlane32_swap_b32_e32 v59, v63
	v_permlane32_swap_b32_e32 v32, v36
	v_permlane32_swap_b32_e32 v33, v37
	v_permlane32_swap_b32_e32 v34, v38
	v_permlane32_swap_b32_e32 v35, v39
	v_permlane32_swap_b32_e32 v40, v44
	v_permlane32_swap_b32_e32 v41, v45
	v_permlane32_swap_b32_e32 v42, v46
	v_permlane32_swap_b32_e32 v43, v47
	v_permlane32_swap_b32_e32 v16, v20
	v_permlane32_swap_b32_e32 v17, v21
	v_permlane32_swap_b32_e32 v18, v22
	v_permlane32_swap_b32_e32 v19, v23
	v_permlane32_swap_b32_e32 v24, v28
	v_permlane32_swap_b32_e32 v25, v29
	v_permlane32_swap_b32_e32 v26, v30
	v_permlane32_swap_b32_e32 v27, v31
	v_permlane32_swap_b32_e32 v0, v4
	v_permlane32_swap_b32_e32 v1, v5
	v_permlane32_swap_b32_e32 v2, v6
	v_permlane32_swap_b32_e32 v3, v7
	v_permlane32_swap_b32_e32 v8, v12
	v_permlane32_swap_b32_e32 v9, v13
	v_permlane32_swap_b32_e32 v10, v14
	v_permlane32_swap_b32_e32 v11, v15
	s_nop 1
	s_branch .LBB0_163

.Lg163_loop:
	s_add_u32 s51, s50, 0x10000
	s_sub_u32 s53, s51, 0x28000
	s_cmp_ge_u32 s51, 0x28000
	s_cselect_b32 s51, s53, s51
	s_add_u32 s52, s49, 0x20000
	s_sub_u32 s53, s52, 0x28000
	s_cmp_ge_u32 s52, 0x28000
	s_cselect_b32 s52, s53, s52
	v_add_u32_e32 v246, s50, v244
	s_waitcnt lgkmcnt(4)
	s_waitcnt lgkmcnt(3)
	v_mfma_f32_16x16x32_bf16 v[112:115], v[192:195], v[224:227], v[112:115]
	v_mfma_f32_16x16x32_bf16 v[120:123], v[196:199], v[224:227], v[120:123]
	v_mfma_f32_16x16x32_bf16 v[96:99], v[200:203], v[224:227], v[96:99]
	v_mfma_f32_16x16x32_bf16 v[104:107], v[204:207], v[224:227], v[104:107]
	s_add_u32 m0, s51, s48
	s_nop 0
	global_load_lds_dwordx4 v248, s[64:65]
	s_add_u32 s64, s64, 0x80
	s_addc_u32 s65, s65, 0
	s_add_u32 s53, s51, s48
	s_add_u32 m0, s53, 0x2000
	s_nop 0
	global_load_lds_dwordx4 v248, s[66:67]
	s_add_u32 s66, s66, 0x80
	s_addc_u32 s67, s67, 0
	ds_read_b128 v[224:227], v245 offset:8192
	s_waitcnt lgkmcnt(3)
	v_mfma_f32_16x16x32_bf16 v[116:119], v[192:195], v[228:231], v[116:119]
	v_mfma_f32_16x16x32_bf16 v[124:127], v[196:199], v[228:231], v[124:127]
	v_mfma_f32_16x16x32_bf16 v[100:103], v[200:203], v[228:231], v[100:103]
	v_mfma_f32_16x16x32_bf16 v[108:111], v[204:207], v[228:231], v[108:111]
	s_add_u32 s53, s51, s48
	s_add_u32 m0, s53, 0x4000
	s_nop 0
	global_load_lds_dwordx4 v248, s[68:69]
	s_add_u32 s68, s68, 0x80
	s_addc_u32 s69, s69, 0
	s_add_u32 s53, s51, s48
	s_add_u32 m0, s53, 0x6000
	s_nop 0
	global_load_lds_dwordx4 v248, s[70:71]
	s_add_u32 s70, s70, 0x80
	s_addc_u32 s71, s71, 0
	ds_read_b128 v[228:231], v245 offset:10240
	s_waitcnt lgkmcnt(3)
	v_mfma_f32_16x16x32_bf16 v[80:83], v[192:195], v[232:235], v[80:83]
	v_mfma_f32_16x16x32_bf16 v[88:91], v[196:199], v[232:235], v[88:91]
	v_mfma_f32_16x16x32_bf16 v[64:67], v[200:203], v[232:235], v[64:67]
	v_mfma_f32_16x16x32_bf16 v[72:75], v[204:207], v[232:235], v[72:75]
	ds_read_b128 v[232:235], v245 offset:12288
	s_waitcnt lgkmcnt(3)
	v_mfma_f32_16x16x32_bf16 v[84:87], v[192:195], v[236:239], v[84:87]
	v_mfma_f32_16x16x32_bf16 v[92:95], v[196:199], v[236:239], v[92:95]
	v_mfma_f32_16x16x32_bf16 v[68:71], v[200:203], v[236:239], v[68:71]
	v_mfma_f32_16x16x32_bf16 v[76:79], v[204:207], v[236:239], v[76:79]
	ds_read_b128 v[236:239], v245 offset:14336
	v_add_u32_e32 v245, s49, v241
	s_waitcnt lgkmcnt(3)
	v_mfma_f32_16x16x32_bf16 v[48:51], v[192:195], v[224:227], v[48:51]
	v_mfma_f32_16x16x32_bf16 v[56:59], v[196:199], v[224:227], v[56:59]
	v_mfma_f32_16x16x32_bf16 v[32:35], v[200:203], v[224:227], v[32:35]
	v_mfma_f32_16x16x32_bf16 v[40:43], v[204:207], v[224:227], v[40:43]
	ds_read_b128 v[224:227], v245
	ds_read_b128 v[208:211], v246
	s_waitcnt lgkmcnt(4)
	v_mfma_f32_16x16x32_bf16 v[52:55], v[192:195], v[228:231], v[52:55]
	v_mfma_f32_16x16x32_bf16 v[60:63], v[196:199], v[228:231], v[60:63]
	v_mfma_f32_16x16x32_bf16 v[36:39], v[200:203], v[228:231], v[36:39]
	v_mfma_f32_16x16x32_bf16 v[44:47], v[204:207], v[228:231], v[44:47]
	ds_read_b128 v[228:231], v245 offset:2048
	ds_read_b128 v[212:215], v246 offset:2048
	s_waitcnt lgkmcnt(5)
	v_mfma_f32_16x16x32_bf16 v[16:19], v[192:195], v[232:235], v[16:19]
	v_mfma_f32_16x16x32_bf16 v[24:27], v[196:199], v[232:235], v[24:27]
	v_mfma_f32_16x16x32_bf16 v[0:3], v[200:203], v[232:235], v[0:3]
	v_mfma_f32_16x16x32_bf16 v[8:11], v[204:207], v[232:235], v[8:11]
	ds_read_b128 v[232:235], v245 offset:4096
	ds_read_b128 v[216:219], v246 offset:4096
	s_waitcnt lgkmcnt(6)
	v_mfma_f32_16x16x32_bf16 v[20:23], v[192:195], v[236:239], v[20:23]
	v_mfma_f32_16x16x32_bf16 v[28:31], v[196:199], v[236:239], v[28:31]
	v_mfma_f32_16x16x32_bf16 v[4:7], v[200:203], v[236:239], v[4:7]
	v_mfma_f32_16x16x32_bf16 v[12:15], v[204:207], v[236:239], v[12:15]
	ds_read_b128 v[236:239], v245 offset:6144
	ds_read_b128 v[220:223], v246 offset:6144
	s_waitcnt lgkmcnt(0)
	v_mfma_f32_16x16x32_bf16 v[112:115], v[208:211], v[224:227], v[112:115]
	v_mfma_f32_16x16x32_bf16 v[120:123], v[212:215], v[224:227], v[120:123]
	v_mfma_f32_16x16x32_bf16 v[96:99], v[216:219], v[224:227], v[96:99]
	v_mfma_f32_16x16x32_bf16 v[104:107], v[220:223], v[224:227], v[104:107]
	ds_read_b128 v[224:227], v245 offset:8192
	v_mfma_f32_16x16x32_bf16 v[116:119], v[208:211], v[228:231], v[116:119]
	v_mfma_f32_16x16x32_bf16 v[124:127], v[212:215], v[228:231], v[124:127]
	v_mfma_f32_16x16x32_bf16 v[100:103], v[216:219], v[228:231], v[100:103]
	v_mfma_f32_16x16x32_bf16 v[108:111], v[220:223], v[228:231], v[108:111]
	ds_read_b128 v[228:231], v245 offset:10240
	v_mfma_f32_16x16x32_bf16 v[80:83], v[208:211], v[232:235], v[80:83]
	v_mfma_f32_16x16x32_bf16 v[88:91], v[212:215], v[232:235], v[88:91]
	v_mfma_f32_16x16x32_bf16 v[64:67], v[216:219], v[232:235], v[64:67]
	v_mfma_f32_16x16x32_bf16 v[72:75], v[220:223], v[232:235], v[72:75]
	ds_read_b128 v[232:235], v245 offset:12288
	v_mfma_f32_16x16x32_bf16 v[84:87], v[208:211], v[236:239], v[84:87]
	v_mfma_f32_16x16x32_bf16 v[92:95], v[212:215], v[236:239], v[92:95]
	v_mfma_f32_16x16x32_bf16 v[68:71], v[216:219], v[236:239], v[68:71]
	v_mfma_f32_16x16x32_bf16 v[76:79], v[220:223], v[236:239], v[76:79]
	ds_read_b128 v[236:239], v245 offset:14336
	s_waitcnt lgkmcnt(3)
	v_mfma_f32_16x16x32_bf16 v[48:51], v[208:211], v[224:227], v[48:51]
	v_mfma_f32_16x16x32_bf16 v[56:59], v[212:215], v[224:227], v[56:59]
	v_mfma_f32_16x16x32_bf16 v[32:35], v[216:219], v[224:227], v[32:35]
	v_mfma_f32_16x16x32_bf16 v[40:43], v[220:223], v[224:227], v[40:43]
	s_add_u32 m0, s52, s48
	s_nop 0
	global_load_lds_dwordx4 v247, s[56:57]
	s_add_u32 s56, s56, 0x80
	s_addc_u32 s57, s57, 0
	s_add_u32 s53, s52, s48
	s_add_u32 m0, s53, 0x2000
	s_nop 0
	global_load_lds_dwordx4 v247, s[58:59]
	s_add_u32 s58, s58, 0x80
	s_addc_u32 s59, s59, 0
	s_waitcnt lgkmcnt(2)
	v_mfma_f32_16x16x32_bf16 v[52:55], v[208:211], v[228:231], v[52:55]
	v_mfma_f32_16x16x32_bf16 v[60:63], v[212:215], v[228:231], v[60:63]
	v_mfma_f32_16x16x32_bf16 v[36:39], v[216:219], v[228:231], v[36:39]
	v_mfma_f32_16x16x32_bf16 v[44:47], v[220:223], v[228:231], v[44:47]
	s_add_u32 s53, s52, s48
	s_add_u32 m0, s53, 0x4000
	s_nop 0
	global_load_lds_dwordx4 v247, s[60:61]
	s_add_u32 s60, s60, 0x80
	s_addc_u32 s61, s61, 0
	s_add_u32 s53, s52, s48
	s_add_u32 m0, s53, 0x6000
	s_nop 0
	global_load_lds_dwordx4 v247, s[62:63]
	s_add_u32 s62, s62, 0x80
	s_addc_u32 s63, s63, 0
	s_waitcnt lgkmcnt(1)
	v_mfma_f32_16x16x32_bf16 v[16:19], v[208:211], v[232:235], v[16:19]
	v_mfma_f32_16x16x32_bf16 v[24:27], v[212:215], v[232:235], v[24:27]
	v_mfma_f32_16x16x32_bf16 v[0:3], v[216:219], v[232:235], v[0:3]
	v_mfma_f32_16x16x32_bf16 v[8:11], v[220:223], v[232:235], v[8:11]
	s_waitcnt lgkmcnt(0)
	s_add_u32 s28, s28, 0x80
	s_addc_u32 s29, s29, 0
	s_add_u32 s49, s49, 0x10000
	s_sub_u32 s53, s49, 0x28000
	s_cmp_ge_u32 s49, 0x28000
	s_cselect_b32 s49, s53, s49
	s_mov_b32 s50, s51
	s_waitcnt vmcnt(4)
	s_barrier
	v_add_u32_e32 v246, s50, v243
	v_add_u32_e32 v245, s49, v240
	ds_read_b128 v[192:195], v246
	ds_read_b128 v[196:199], v246 offset:2048
	ds_read_b128 v[200:203], v246 offset:4096
	ds_read_b128 v[204:207], v246 offset:6144
	ds_read_b128 v[224:227], v245
	ds_read_b128 v[228:231], v245 offset:2048
	ds_read_b128 v[232:235], v245 offset:4096
	v_mfma_f32_16x16x32_bf16 v[20:23], v[208:211], v[236:239], v[20:23]
	v_mfma_f32_16x16x32_bf16 v[28:31], v[212:215], v[236:239], v[28:31]
	v_mfma_f32_16x16x32_bf16 v[4:7], v[216:219], v[236:239], v[4:7]
	v_mfma_f32_16x16x32_bf16 v[12:15], v[220:223], v[236:239], v[12:15]
	ds_read_b128 v[236:239], v245 offset:6144
	s_cmpk_lg_i32 s28, 0xf00
	s_cbranch_scc1 .Lg163_loop
	s_add_u32 s51, s50, 0x10000
	s_sub_u32 s53, s51, 0x28000
	s_cmp_ge_u32 s51, 0x28000
	s_cselect_b32 s51, s53, s51
	v_add_u32_e32 v246, s50, v244
	s_waitcnt lgkmcnt(4)
	s_waitcnt lgkmcnt(3)
	v_mfma_f32_16x16x32_bf16 v[112:115], v[192:195], v[224:227], v[112:115]
	v_mfma_f32_16x16x32_bf16 v[120:123], v[196:199], v[224:227], v[120:123]
	v_mfma_f32_16x16x32_bf16 v[96:99], v[200:203], v[224:227], v[96:99]
	v_mfma_f32_16x16x32_bf16 v[104:107], v[204:207], v[224:227], v[104:107]
	s_add_u32 m0, s51, s48
	s_nop 0
	global_load_lds_dwordx4 v248, s[64:65]
	s_add_u32 s64, s64, 0x80
	s_addc_u32 s65, s65, 0
	s_add_u32 s53, s51, s48
	s_add_u32 m0, s53, 0x2000
	s_nop 0
	global_load_lds_dwordx4 v248, s[66:67]
	s_add_u32 s66, s66, 0x80
	s_addc_u32 s67, s67, 0
	ds_read_b128 v[224:227], v245 offset:8192
	s_waitcnt lgkmcnt(3)
	v_mfma_f32_16x16x32_bf16 v[116:119], v[192:195], v[228:231], v[116:119]
	v_mfma_f32_16x16x32_bf16 v[124:127], v[196:199], v[228:231], v[124:127]
	v_mfma_f32_16x16x32_bf16 v[100:103], v[200:203], v[228:231], v[100:103]
	v_mfma_f32_16x16x32_bf16 v[108:111], v[204:207], v[228:231], v[108:111]
	s_add_u32 s53, s51, s48
	s_add_u32 m0, s53, 0x4000
	s_nop 0
	global_load_lds_dwordx4 v248, s[68:69]
	s_add_u32 s68, s68, 0x80
	s_addc_u32 s69, s69, 0
	s_add_u32 s53, s51, s48
	s_add_u32 m0, s53, 0x6000
	s_nop 0
	global_load_lds_dwordx4 v248, s[70:71]
	s_add_u32 s70, s70, 0x80
	s_addc_u32 s71, s71, 0
	ds_read_b128 v[228:231], v245 offset:10240
	s_waitcnt lgkmcnt(3)
	v_mfma_f32_16x16x32_bf16 v[80:83], v[192:195], v[232:235], v[80:83]
	v_mfma_f32_16x16x32_bf16 v[88:91], v[196:199], v[232:235], v[88:91]
	v_mfma_f32_16x16x32_bf16 v[64:67], v[200:203], v[232:235], v[64:67]
	v_mfma_f32_16x16x32_bf16 v[72:75], v[204:207], v[232:235], v[72:75]
	ds_read_b128 v[232:235], v245 offset:12288
	s_waitcnt lgkmcnt(3)
	v_mfma_f32_16x16x32_bf16 v[84:87], v[192:195], v[236:239], v[84:87]
	v_mfma_f32_16x16x32_bf16 v[92:95], v[196:199], v[236:239], v[92:95]
	v_mfma_f32_16x16x32_bf16 v[68:71], v[200:203], v[236:239], v[68:71]
	v_mfma_f32_16x16x32_bf16 v[76:79], v[204:207], v[236:239], v[76:79]
	ds_read_b128 v[236:239], v245 offset:14336
	v_add_u32_e32 v245, s49, v241
	s_waitcnt lgkmcnt(3)
	v_mfma_f32_16x16x32_bf16 v[48:51], v[192:195], v[224:227], v[48:51]
	v_mfma_f32_16x16x32_bf16 v[56:59], v[196:199], v[224:227], v[56:59]
	v_mfma_f32_16x16x32_bf16 v[32:35], v[200:203], v[224:227], v[32:35]
	v_mfma_f32_16x16x32_bf16 v[40:43], v[204:207], v[224:227], v[40:43]
	ds_read_b128 v[224:227], v245
	ds_read_b128 v[208:211], v246
	s_waitcnt lgkmcnt(4)
	v_mfma_f32_16x16x32_bf16 v[52:55], v[192:195], v[228:231], v[52:55]
	v_mfma_f32_16x16x32_bf16 v[60:63], v[196:199], v[228:231], v[60:63]
	v_mfma_f32_16x16x32_bf16 v[36:39], v[200:203], v[228:231], v[36:39]
	v_mfma_f32_16x16x32_bf16 v[44:47], v[204:207], v[228:231], v[44:47]
	ds_read_b128 v[228:231], v245 offset:2048
	ds_read_b128 v[212:215], v246 offset:2048
	s_waitcnt lgkmcnt(5)
	v_mfma_f32_16x16x32_bf16 v[16:19], v[192:195], v[232:235], v[16:19]
	v_mfma_f32_16x16x32_bf16 v[24:27], v[196:199], v[232:235], v[24:27]
	v_mfma_f32_16x16x32_bf16 v[0:3], v[200:203], v[232:235], v[0:3]
	v_mfma_f32_16x16x32_bf16 v[8:11], v[204:207], v[232:235], v[8:11]
	ds_read_b128 v[232:235], v245 offset:4096
	ds_read_b128 v[216:219], v246 offset:4096
	s_waitcnt lgkmcnt(6)
	v_mfma_f32_16x16x32_bf16 v[20:23], v[192:195], v[236:239], v[20:23]
	v_mfma_f32_16x16x32_bf16 v[28:31], v[196:199], v[236:239], v[28:31]
	v_mfma_f32_16x16x32_bf16 v[4:7], v[200:203], v[236:239], v[4:7]
	v_mfma_f32_16x16x32_bf16 v[12:15], v[204:207], v[236:239], v[12:15]
	ds_read_b128 v[236:239], v245 offset:6144
	ds_read_b128 v[220:223], v246 offset:6144
	s_waitcnt lgkmcnt(0)
	v_mfma_f32_16x16x32_bf16 v[112:115], v[208:211], v[224:227], v[112:115]
	v_mfma_f32_16x16x32_bf16 v[120:123], v[212:215], v[224:227], v[120:123]
	v_mfma_f32_16x16x32_bf16 v[96:99], v[216:219], v[224:227], v[96:99]
	v_mfma_f32_16x16x32_bf16 v[104:107], v[220:223], v[224:227], v[104:107]
	ds_read_b128 v[224:227], v245 offset:8192
	v_mfma_f32_16x16x32_bf16 v[116:119], v[208:211], v[228:231], v[116:119]
	v_mfma_f32_16x16x32_bf16 v[124:127], v[212:215], v[228:231], v[124:127]
	v_mfma_f32_16x16x32_bf16 v[100:103], v[216:219], v[228:231], v[100:103]
	v_mfma_f32_16x16x32_bf16 v[108:111], v[220:223], v[228:231], v[108:111]
	ds_read_b128 v[228:231], v245 offset:10240
	v_mfma_f32_16x16x32_bf16 v[80:83], v[208:211], v[232:235], v[80:83]
	v_mfma_f32_16x16x32_bf16 v[88:91], v[212:215], v[232:235], v[88:91]
	v_mfma_f32_16x16x32_bf16 v[64:67], v[216:219], v[232:235], v[64:67]
	v_mfma_f32_16x16x32_bf16 v[72:75], v[220:223], v[232:235], v[72:75]
	ds_read_b128 v[232:235], v245 offset:12288
	v_mfma_f32_16x16x32_bf16 v[84:87], v[208:211], v[236:239], v[84:87]
	v_mfma_f32_16x16x32_bf16 v[92:95], v[212:215], v[236:239], v[92:95]
	v_mfma_f32_16x16x32_bf16 v[68:71], v[216:219], v[236:239], v[68:71]
	v_mfma_f32_16x16x32_bf16 v[76:79], v[220:223], v[236:239], v[76:79]
	ds_read_b128 v[236:239], v245 offset:14336
	s_waitcnt lgkmcnt(3)
	v_mfma_f32_16x16x32_bf16 v[48:51], v[208:211], v[224:227], v[48:51]
	v_mfma_f32_16x16x32_bf16 v[56:59], v[212:215], v[224:227], v[56:59]
	v_mfma_f32_16x16x32_bf16 v[32:35], v[216:219], v[224:227], v[32:35]
	v_mfma_f32_16x16x32_bf16 v[40:43], v[220:223], v[224:227], v[40:43]
	s_waitcnt lgkmcnt(2)
	v_mfma_f32_16x16x32_bf16 v[52:55], v[208:211], v[228:231], v[52:55]
	v_mfma_f32_16x16x32_bf16 v[60:63], v[212:215], v[228:231], v[60:63]
	v_mfma_f32_16x16x32_bf16 v[36:39], v[216:219], v[228:231], v[36:39]
	v_mfma_f32_16x16x32_bf16 v[44:47], v[220:223], v[228:231], v[44:47]
	s_waitcnt lgkmcnt(1)
	v_mfma_f32_16x16x32_bf16 v[16:19], v[208:211], v[232:235], v[16:19]
	v_mfma_f32_16x16x32_bf16 v[24:27], v[212:215], v[232:235], v[24:27]
	v_mfma_f32_16x16x32_bf16 v[0:3], v[216:219], v[232:235], v[0:3]
	v_mfma_f32_16x16x32_bf16 v[8:11], v[220:223], v[232:235], v[8:11]
	s_waitcnt lgkmcnt(0)
	s_add_u32 s28, s28, 0x80
	s_addc_u32 s29, s29, 0
	s_add_u32 s49, s49, 0x10000
	s_sub_u32 s53, s49, 0x28000
	s_cmp_ge_u32 s49, 0x28000
	s_cselect_b32 s49, s53, s49
	s_mov_b32 s50, s51
	s_waitcnt vmcnt(0)
	s_barrier
	v_add_u32_e32 v246, s50, v243
	v_add_u32_e32 v245, s49, v240
	ds_read_b128 v[192:195], v246
	ds_read_b128 v[196:199], v246 offset:2048
	ds_read_b128 v[200:203], v246 offset:4096
	ds_read_b128 v[204:207], v246 offset:6144
	ds_read_b128 v[224:227], v245
	ds_read_b128 v[228:231], v245 offset:2048
	ds_read_b128 v[232:235], v245 offset:4096
	v_mfma_f32_16x16x32_bf16 v[20:23], v[208:211], v[236:239], v[20:23]
	v_mfma_f32_16x16x32_bf16 v[28:31], v[212:215], v[236:239], v[28:31]
	v_mfma_f32_16x16x32_bf16 v[4:7], v[216:219], v[236:239], v[4:7]
	v_mfma_f32_16x16x32_bf16 v[12:15], v[220:223], v[236:239], v[12:15]
	ds_read_b128 v[236:239], v245 offset:6144
	v_add_u32_e32 v246, s50, v244
	s_waitcnt lgkmcnt(4)
	s_waitcnt lgkmcnt(3)
	v_mfma_f32_16x16x32_bf16 v[112:115], v[192:195], v[224:227], v[112:115]
	v_mfma_f32_16x16x32_bf16 v[120:123], v[196:199], v[224:227], v[120:123]
	v_mfma_f32_16x16x32_bf16 v[96:99], v[200:203], v[224:227], v[96:99]
	v_mfma_f32_16x16x32_bf16 v[104:107], v[204:207], v[224:227], v[104:107]
	ds_read_b128 v[224:227], v245 offset:8192
	s_waitcnt lgkmcnt(3)
	v_mfma_f32_16x16x32_bf16 v[116:119], v[192:195], v[228:231], v[116:119]
	v_mfma_f32_16x16x32_bf16 v[124:127], v[196:199], v[228:231], v[124:127]
	v_mfma_f32_16x16x32_bf16 v[100:103], v[200:203], v[228:231], v[100:103]
	v_mfma_f32_16x16x32_bf16 v[108:111], v[204:207], v[228:231], v[108:111]
	ds_read_b128 v[228:231], v245 offset:10240
	s_waitcnt lgkmcnt(3)
	v_mfma_f32_16x16x32_bf16 v[80:83], v[192:195], v[232:235], v[80:83]
	v_mfma_f32_16x16x32_bf16 v[88:91], v[196:199], v[232:235], v[88:91]
	v_mfma_f32_16x16x32_bf16 v[64:67], v[200:203], v[232:235], v[64:67]
	v_mfma_f32_16x16x32_bf16 v[72:75], v[204:207], v[232:235], v[72:75]
	ds_read_b128 v[232:235], v245 offset:12288
	s_waitcnt lgkmcnt(3)
	v_mfma_f32_16x16x32_bf16 v[84:87], v[192:195], v[236:239], v[84:87]
	v_mfma_f32_16x16x32_bf16 v[92:95], v[196:199], v[236:239], v[92:95]
	v_mfma_f32_16x16x32_bf16 v[68:71], v[200:203], v[236:239], v[68:71]
	v_mfma_f32_16x16x32_bf16 v[76:79], v[204:207], v[236:239], v[76:79]
	ds_read_b128 v[236:239], v245 offset:14336
	v_add_u32_e32 v245, s49, v241
	s_waitcnt lgkmcnt(3)
	v_mfma_f32_16x16x32_bf16 v[48:51], v[192:195], v[224:227], v[48:51]
	v_mfma_f32_16x16x32_bf16 v[56:59], v[196:199], v[224:227], v[56:59]
	v_mfma_f32_16x16x32_bf16 v[32:35], v[200:203], v[224:227], v[32:35]
	v_mfma_f32_16x16x32_bf16 v[40:43], v[204:207], v[224:227], v[40:43]
	ds_read_b128 v[224:227], v245
	ds_read_b128 v[208:211], v246
	s_waitcnt lgkmcnt(4)
	v_mfma_f32_16x16x32_bf16 v[52:55], v[192:195], v[228:231], v[52:55]
	v_mfma_f32_16x16x32_bf16 v[60:63], v[196:199], v[228:231], v[60:63]
	v_mfma_f32_16x16x32_bf16 v[36:39], v[200:203], v[228:231], v[36:39]
	v_mfma_f32_16x16x32_bf16 v[44:47], v[204:207], v[228:231], v[44:47]
	ds_read_b128 v[228:231], v245 offset:2048
	ds_read_b128 v[212:215], v246 offset:2048
	s_waitcnt lgkmcnt(5)
	v_mfma_f32_16x16x32_bf16 v[16:19], v[192:195], v[232:235], v[16:19]
	v_mfma_f32_16x16x32_bf16 v[24:27], v[196:199], v[232:235], v[24:27]
	v_mfma_f32_16x16x32_bf16 v[0:3], v[200:203], v[232:235], v[0:3]
	v_mfma_f32_16x16x32_bf16 v[8:11], v[204:207], v[232:235], v[8:11]
	ds_read_b128 v[232:235], v245 offset:4096
	ds_read_b128 v[216:219], v246 offset:4096
	s_waitcnt lgkmcnt(6)
	v_mfma_f32_16x16x32_bf16 v[20:23], v[192:195], v[236:239], v[20:23]
	v_mfma_f32_16x16x32_bf16 v[28:31], v[196:199], v[236:239], v[28:31]
	v_mfma_f32_16x16x32_bf16 v[4:7], v[200:203], v[236:239], v[4:7]
	v_mfma_f32_16x16x32_bf16 v[12:15], v[204:207], v[236:239], v[12:15]
	ds_read_b128 v[236:239], v245 offset:6144
	ds_read_b128 v[220:223], v246 offset:6144
	s_waitcnt lgkmcnt(0)
	v_mfma_f32_16x16x32_bf16 v[112:115], v[208:211], v[224:227], v[112:115]
	v_mfma_f32_16x16x32_bf16 v[120:123], v[212:215], v[224:227], v[120:123]
	v_mfma_f32_16x16x32_bf16 v[96:99], v[216:219], v[224:227], v[96:99]
	v_mfma_f32_16x16x32_bf16 v[104:107], v[220:223], v[224:227], v[104:107]
	ds_read_b128 v[224:227], v245 offset:8192
	v_mfma_f32_16x16x32_bf16 v[116:119], v[208:211], v[228:231], v[116:119]
	v_mfma_f32_16x16x32_bf16 v[124:127], v[212:215], v[228:231], v[124:127]
	v_mfma_f32_16x16x32_bf16 v[100:103], v[216:219], v[228:231], v[100:103]
	v_mfma_f32_16x16x32_bf16 v[108:111], v[220:223], v[228:231], v[108:111]
	ds_read_b128 v[228:231], v245 offset:10240
	v_mfma_f32_16x16x32_bf16 v[80:83], v[208:211], v[232:235], v[80:83]
	v_mfma_f32_16x16x32_bf16 v[88:91], v[212:215], v[232:235], v[88:91]
	v_mfma_f32_16x16x32_bf16 v[64:67], v[216:219], v[232:235], v[64:67]
	v_mfma_f32_16x16x32_bf16 v[72:75], v[220:223], v[232:235], v[72:75]
	ds_read_b128 v[232:235], v245 offset:12288
	v_mfma_f32_16x16x32_bf16 v[84:87], v[208:211], v[236:239], v[84:87]
	v_mfma_f32_16x16x32_bf16 v[92:95], v[212:215], v[236:239], v[92:95]
	v_mfma_f32_16x16x32_bf16 v[68:71], v[216:219], v[236:239], v[68:71]
	v_mfma_f32_16x16x32_bf16 v[76:79], v[220:223], v[236:239], v[76:79]
	ds_read_b128 v[236:239], v245 offset:14336
	s_waitcnt lgkmcnt(3)
	v_mfma_f32_16x16x32_bf16 v[48:51], v[208:211], v[224:227], v[48:51]
	v_mfma_f32_16x16x32_bf16 v[56:59], v[212:215], v[224:227], v[56:59]
	v_mfma_f32_16x16x32_bf16 v[32:35], v[216:219], v[224:227], v[32:35]
	v_mfma_f32_16x16x32_bf16 v[40:43], v[220:223], v[224:227], v[40:43]
	s_waitcnt lgkmcnt(2)
	v_mfma_f32_16x16x32_bf16 v[52:55], v[208:211], v[228:231], v[52:55]
	v_mfma_f32_16x16x32_bf16 v[60:63], v[212:215], v[228:231], v[60:63]
	v_mfma_f32_16x16x32_bf16 v[36:39], v[216:219], v[228:231], v[36:39]
	v_mfma_f32_16x16x32_bf16 v[44:47], v[220:223], v[228:231], v[44:47]
	s_waitcnt lgkmcnt(1)
	v_mfma_f32_16x16x32_bf16 v[16:19], v[208:211], v[232:235], v[16:19]
	v_mfma_f32_16x16x32_bf16 v[24:27], v[212:215], v[232:235], v[24:27]
	v_mfma_f32_16x16x32_bf16 v[0:3], v[216:219], v[232:235], v[0:3]
	v_mfma_f32_16x16x32_bf16 v[8:11], v[220:223], v[232:235], v[8:11]
	s_waitcnt lgkmcnt(0)
	s_waitcnt vmcnt(0)
	s_barrier
	v_mfma_f32_16x16x32_bf16 v[20:23], v[208:211], v[236:239], v[20:23]
	v_mfma_f32_16x16x32_bf16 v[28:31], v[212:215], v[236:239], v[28:31]
	v_mfma_f32_16x16x32_bf16 v[4:7], v[216:219], v[236:239], v[4:7]
	v_mfma_f32_16x16x32_bf16 v[12:15], v[220:223], v[236:239], v[12:15]
	s_nop 15
	v_permlane16_swap_b32_e32 v112, v116
	v_permlane16_swap_b32_e32 v113, v117
	v_permlane16_swap_b32_e32 v114, v118
	v_permlane16_swap_b32_e32 v115, v119
	v_permlane16_swap_b32_e32 v120, v124
	v_permlane16_swap_b32_e32 v121, v125
	v_permlane16_swap_b32_e32 v122, v126
	v_permlane16_swap_b32_e32 v123, v127
	v_permlane16_swap_b32_e32 v96, v100
	v_permlane16_swap_b32_e32 v97, v101
	v_permlane16_swap_b32_e32 v98, v102
	v_permlane16_swap_b32_e32 v99, v103
	v_permlane16_swap_b32_e32 v104, v108
	v_permlane16_swap_b32_e32 v105, v109
	v_permlane16_swap_b32_e32 v106, v110
	v_permlane16_swap_b32_e32 v107, v111
	v_permlane16_swap_b32_e32 v80, v84
	v_permlane16_swap_b32_e32 v81, v85
	v_permlane16_swap_b32_e32 v82, v86
	v_permlane16_swap_b32_e32 v83, v87
	v_permlane16_swap_b32_e32 v88, v92
	v_permlane16_swap_b32_e32 v89, v93
	v_permlane16_swap_b32_e32 v90, v94
	v_permlane16_swap_b32_e32 v91, v95
	v_permlane16_swap_b32_e32 v64, v68
	v_permlane16_swap_b32_e32 v65, v69
	v_permlane16_swap_b32_e32 v66, v70
	v_permlane16_swap_b32_e32 v67, v71
	v_permlane16_swap_b32_e32 v72, v76
	v_permlane16_swap_b32_e32 v73, v77
	v_permlane16_swap_b32_e32 v74, v78
	v_permlane16_swap_b32_e32 v75, v79
	v_permlane16_swap_b32_e32 v48, v52
	v_permlane16_swap_b32_e32 v49, v53
	v_permlane16_swap_b32_e32 v50, v54
	v_permlane16_swap_b32_e32 v51, v55
	v_permlane16_swap_b32_e32 v56, v60
	v_permlane16_swap_b32_e32 v57, v61
	v_permlane16_swap_b32_e32 v58, v62
	v_permlane16_swap_b32_e32 v59, v63
	v_permlane16_swap_b32_e32 v32, v36
	v_permlane16_swap_b32_e32 v33, v37
	v_permlane16_swap_b32_e32 v34, v38
	v_permlane16_swap_b32_e32 v35, v39
	v_permlane16_swap_b32_e32 v40, v44
	v_permlane16_swap_b32_e32 v41, v45
	v_permlane16_swap_b32_e32 v42, v46
	v_permlane16_swap_b32_e32 v43, v47
	v_permlane16_swap_b32_e32 v16, v20
	v_permlane16_swap_b32_e32 v17, v21
	v_permlane16_swap_b32_e32 v18, v22
	v_permlane16_swap_b32_e32 v19, v23
	v_permlane16_swap_b32_e32 v24, v28
	v_permlane16_swap_b32_e32 v25, v29
	v_permlane16_swap_b32_e32 v26, v30
	v_permlane16_swap_b32_e32 v27, v31
	v_permlane16_swap_b32_e32 v0, v4
	v_permlane16_swap_b32_e32 v1, v5
	v_permlane16_swap_b32_e32 v2, v6
	v_permlane16_swap_b32_e32 v3, v7
	v_permlane16_swap_b32_e32 v8, v12
	v_permlane16_swap_b32_e32 v9, v13
	v_permlane16_swap_b32_e32 v10, v14
	v_permlane16_swap_b32_e32 v11, v15
	v_permlane32_swap_b32_e32 v112, v116
	v_permlane32_swap_b32_e32 v113, v117
	v_permlane32_swap_b32_e32 v114, v118
	v_permlane32_swap_b32_e32 v115, v119
	v_permlane32_swap_b32_e32 v120, v124
	v_permlane32_swap_b32_e32 v121, v125
	v_permlane32_swap_b32_e32 v122, v126
	v_permlane32_swap_b32_e32 v123, v127
	v_permlane32_swap_b32_e32 v96, v100
	v_permlane32_swap_b32_e32 v97, v101
	v_permlane32_swap_b32_e32 v98, v102
	v_permlane32_swap_b32_e32 v99, v103
	v_permlane32_swap_b32_e32 v104, v108
	v_permlane32_swap_b32_e32 v105, v109
	v_permlane32_swap_b32_e32 v106, v110
	v_permlane32_swap_b32_e32 v107, v111
	v_permlane32_swap_b32_e32 v80, v84
	v_permlane32_swap_b32_e32 v81, v85
	v_permlane32_swap_b32_e32 v82, v86
	v_permlane32_swap_b32_e32 v83, v87
	v_permlane32_swap_b32_e32 v88, v92
	v_permlane32_swap_b32_e32 v89, v93
	v_permlane32_swap_b32_e32 v90, v94
	v_permlane32_swap_b32_e32 v91, v95
	v_permlane32_swap_b32_e32 v64, v68
	v_permlane32_swap_b32_e32 v65, v69
	v_permlane32_swap_b32_e32 v66, v70
	v_permlane32_swap_b32_e32 v67, v71
	v_permlane32_swap_b32_e32 v72, v76
	v_permlane32_swap_b32_e32 v73, v77
	v_permlane32_swap_b32_e32 v74, v78
	v_permlane32_swap_b32_e32 v75, v79
	v_permlane32_swap_b32_e32 v48, v52
	v_permlane32_swap_b32_e32 v49, v53
	v_permlane32_swap_b32_e32 v50, v54
	v_permlane32_swap_b32_e32 v51, v55
	v_permlane32_swap_b32_e32 v56, v60
	v_permlane32_swap_b32_e32 v57, v61
	v_permlane32_swap_b32_e32 v58, v62
	v_permlane32_swap_b32_e32 v59, v63
	v_permlane32_swap_b32_e32 v32, v36
	v_permlane32_swap_b32_e32 v33, v37
	v_permlane32_swap_b32_e32 v34, v38
	v_permlane32_swap_b32_e32 v35, v39
	v_permlane32_swap_b32_e32 v40, v44
	v_permlane32_swap_b32_e32 v41, v45
	v_permlane32_swap_b32_e32 v42, v46
	v_permlane32_swap_b32_e32 v43, v47
	v_permlane32_swap_b32_e32 v16, v20
	v_permlane32_swap_b32_e32 v17, v21
	v_permlane32_swap_b32_e32 v18, v22
	v_permlane32_swap_b32_e32 v19, v23
	v_permlane32_swap_b32_e32 v24, v28
	v_permlane32_swap_b32_e32 v25, v29
	v_permlane32_swap_b32_e32 v26, v30
	v_permlane32_swap_b32_e32 v27, v31
	v_permlane32_swap_b32_e32 v0, v4
	v_permlane32_swap_b32_e32 v1, v5
	v_permlane32_swap_b32_e32 v2, v6
	v_permlane32_swap_b32_e32 v3, v7
	v_permlane32_swap_b32_e32 v8, v12
	v_permlane32_swap_b32_e32 v9, v13
	v_permlane32_swap_b32_e32 v10, v14
	v_permlane32_swap_b32_e32 v11, v15
	s_nop 1
